# non-temporal (nt) hint on all 224 GEMM epilogue stores, on top of the arrival-time-invalidate barrier
# baseline (speedup 1.0000x reference)
.LBB0_220:
	v_lshl_add_u32 v144, s48, 8, v146
	v_lshl_or_b32 v142, s83, 8, v148
	v_ashrrev_i32_e32 v145, 31, v144
	v_ashrrev_i32_e32 v143, 31, v142
	v_lshlrev_b64 v[150:151], 13, v[144:145]
	v_lshl_add_u64 v[150:151], s[70:71], 0, v[150:151]
	v_lshlrev_b64 v[152:153], 1, v[142:143]
	v_lshl_add_u64 v[142:143], v[150:151], 0, v[152:153]
	v_cvt_pk_bf16_f32 v126, v126, v127
	v_cvt_pk_bf16_f32 v127, v128, v129
	v_cvt_pk_bf16_f32 v128, v122, v123
	v_cvt_pk_bf16_f32 v129, v124, v125
	global_store_dwordx4 v[142:143], v[126:129], off nt
	v_cvt_pk_bf16_f32 v114, v114, v115
	v_cvt_pk_bf16_f32 v115, v116, v117
	v_cvt_pk_bf16_f32 v116, v106, v107
	v_or_b32_e32 v106, 16, v144
	v_ashrrev_i32_e32 v107, 31, v106
	v_lshlrev_b64 v[106:107], 13, v[106:107]
	v_lshl_add_u64 v[106:107], s[70:71], 0, v[106:107]
	v_cvt_pk_bf16_f32 v117, v108, v109
	global_store_dwordx4 v[142:143], v[114:117], off offset:256 nt
	s_mov_b64 s[28:29], 0x100000
	s_nop 0
	v_lshl_add_u64 v[114:115], v[106:107], 0, v[152:153]
	v_cvt_pk_bf16_f32 v106, v118, v119
	v_cvt_pk_bf16_f32 v107, v120, v121
	v_cvt_pk_bf16_f32 v108, v110, v111
	v_cvt_pk_bf16_f32 v109, v112, v113
	global_store_dwordx4 v[114:115], v[106:109], off nt
	v_cvt_pk_bf16_f32 v98, v98, v99
	v_cvt_pk_bf16_f32 v99, v100, v101
	v_cvt_pk_bf16_f32 v100, v90, v91
	v_or_b32_e32 v90, 32, v144
	v_ashrrev_i32_e32 v91, 31, v90
	v_lshlrev_b64 v[90:91], 13, v[90:91]
	v_lshl_add_u64 v[90:91], s[70:71], 0, v[90:91]
	v_cvt_pk_bf16_f32 v101, v92, v93
	global_store_dwordx4 v[114:115], v[98:101], off offset:256 nt
	s_nop 1
	v_lshl_add_u64 v[98:99], v[90:91], 0, v[152:153]
	v_cvt_pk_bf16_f32 v90, v102, v103
	v_cvt_pk_bf16_f32 v91, v104, v105
	v_cvt_pk_bf16_f32 v92, v94, v95
	v_cvt_pk_bf16_f32 v93, v96, v97
	global_store_dwordx4 v[98:99], v[90:93], off nt
	v_cvt_pk_bf16_f32 v82, v82, v83
	v_cvt_pk_bf16_f32 v83, v84, v85
	v_cvt_pk_bf16_f32 v84, v74, v75
	v_or_b32_e32 v74, 48, v144
	v_ashrrev_i32_e32 v75, 31, v74
	v_lshlrev_b64 v[74:75], 13, v[74:75]
	v_lshl_add_u64 v[74:75], s[70:71], 0, v[74:75]
	v_cvt_pk_bf16_f32 v85, v76, v77
	global_store_dwordx4 v[98:99], v[82:85], off offset:256 nt
	s_nop 1
	v_lshl_add_u64 v[82:83], v[74:75], 0, v[152:153]
	v_cvt_pk_bf16_f32 v74, v86, v87
	v_cvt_pk_bf16_f32 v75, v88, v89
	v_cvt_pk_bf16_f32 v76, v78, v79
	v_cvt_pk_bf16_f32 v77, v80, v81
	global_store_dwordx4 v[82:83], v[74:77], off nt
	v_cvt_pk_bf16_f32 v70, v70, v71
	v_cvt_pk_bf16_f32 v71, v72, v73
	v_cvt_pk_bf16_f32 v72, v66, v67
	v_lshl_add_u64 v[66:67], v[142:143], 0, s[28:29]
	s_mov_b32 s28, 0x100000
	v_cvt_pk_bf16_f32 v73, v68, v69
	global_store_dwordx4 v[82:83], v[70:73], off offset:256 nt
	v_cvt_pk_bf16_f32 v62, v62, v63
	v_cvt_pk_bf16_f32 v63, v64, v65
	v_cvt_pk_bf16_f32 v64, v58, v59
	v_add_co_u32_e32 v58, vcc, s28, v142
	v_cvt_pk_bf16_f32 v65, v60, v61
	s_mov_b64 s[28:29], 0x120000
	s_nop 0
	v_addc_co_u32_e32 v59, vcc, 0, v143, vcc
	global_store_dwordx4 v[58:59], v[62:65], off nt
	v_cvt_pk_bf16_f32 v50, v50, v51
	v_cvt_pk_bf16_f32 v51, v52, v53
	v_cvt_pk_bf16_f32 v52, v42, v43
	v_cvt_pk_bf16_f32 v53, v44, v45
	global_store_dwordx4 v[66:67], v[50:53], off offset:256 nt
	v_cvt_pk_bf16_f32 v42, v54, v55
	v_cvt_pk_bf16_f32 v43, v56, v57
	v_cvt_pk_bf16_f32 v44, v46, v47
	v_cvt_pk_bf16_f32 v45, v48, v49
	s_nop 1
	v_lshl_add_u64 v[50:51], v[142:143], 0, s[28:29]
	s_mov_b32 s28, 0x120000
	v_add_co_u32_e32 v46, vcc, s28, v142
	s_mov_b64 s[28:29], 0x140000
	s_nop 0
	v_addc_co_u32_e32 v47, vcc, 0, v143, vcc
	global_store_dwordx4 v[46:47], v[42:45], off nt
	v_cvt_pk_bf16_f32 v34, v34, v35
	v_cvt_pk_bf16_f32 v35, v36, v37
	v_cvt_pk_bf16_f32 v36, v26, v27
	v_cvt_pk_bf16_f32 v37, v28, v29
	global_store_dwordx4 v[50:51], v[34:37], off offset:256 nt
	v_cvt_pk_bf16_f32 v26, v38, v39
	v_cvt_pk_bf16_f32 v27, v40, v41
	v_cvt_pk_bf16_f32 v28, v30, v31
	v_cvt_pk_bf16_f32 v29, v32, v33
	s_nop 1
	v_lshl_add_u64 v[34:35], v[142:143], 0, s[28:29]
	s_mov_b32 s28, 0x140000
	v_add_co_u32_e32 v30, vcc, s28, v142
	s_mov_b64 s[28:29], 0x160000
	s_nop 0
	v_addc_co_u32_e32 v31, vcc, 0, v143, vcc
	global_store_dwordx4 v[30:31], v[26:29], off nt
	v_cvt_pk_bf16_f32 v18, v18, v19
	v_cvt_pk_bf16_f32 v19, v20, v21
	v_cvt_pk_bf16_f32 v20, v8, v9
	v_cvt_pk_bf16_f32 v21, v10, v11
	global_store_dwordx4 v[34:35], v[18:21], off offset:256 nt
	v_cvt_pk_bf16_f32 v8, v22, v23
	v_cvt_pk_bf16_f32 v9, v24, v25
	v_cvt_pk_bf16_f32 v10, v12, v13
	v_cvt_pk_bf16_f32 v11, v14, v15
	s_nop 1
	v_lshl_add_u64 v[18:19], v[142:143], 0, s[28:29]
	s_mov_b32 s28, 0x160000
	v_add_co_u32_e32 v12, vcc, s28, v142
	s_nop 1
	v_addc_co_u32_e32 v13, vcc, 0, v143, vcc
	global_store_dwordx4 v[12:13], v[8:11], off nt
	v_cvt_pk_bf16_f32 v4, v4, v5
	v_cvt_pk_bf16_f32 v5, v6, v7
	v_cvt_pk_bf16_f32 v6, v0, v1
	v_cvt_pk_bf16_f32 v7, v2, v3
	global_store_dwordx4 v[18:19], v[4:7], off offset:256 nt
	s_andn2_b64 vcc, exec, s[38:39]
	s_mov_b64 s[28:29], -1
	s_cbranch_vccnz .LBB0_212
	s_branch .LBB0_224

.LBB0_222:
	s_lshl_b32 s41, s48, 8
	s_ashr_i32 s28, s48, 3
	s_sub_i32 s29, s48, 64
	s_and_b32 s41, s41, 0x700
	s_cmp_lt_i32 s48, 64
	s_cselect_b32 s50, s28, s29
	s_mov_b32 s28, 0x27d78000
	s_cselect_b32 s29, s41, 0
	s_cselect_b32 s41, s28, 0x28d78000
	v_readlane_b32 s52, v254, 0
	s_cselect_b32 s28, 11, 8
	v_readlane_b32 s53, v254, 1
	s_add_u32 s41, s52, s41
	s_addc_u32 s43, s53, 0
	s_ashr_i32 s51, s50, 31
	s_lshl_b64 s[50:51], s[50:51], 9
	s_lshl_b32 s29, s29, 1
	s_add_u32 s29, s41, s29
	s_addc_u32 s41, s43, 0
	s_add_u32 s52, s29, s22
	s_addc_u32 s53, s41, s23
	s_lshl_b32 s29, s83, 8
	s_addk_i32 s29, 0xf200
	v_or_b32_e32 v144, s29, v148
	v_mov_b32_e32 v145, v17
	v_lshl_add_u64 v[150:151], s[50:51], 0, v[144:145]
	v_lshl_add_u64 v[142:143], s[52:53], 0, v[16:17]
	v_lshlrev_b64 v[150:151], s28, v[150:151]
	v_lshl_add_u64 v[150:151], v[150:151], 1, v[142:143]
	v_cvt_pk_bf16_f32 v145, v126, v17
	global_store_short v[150:151], v145, off nt
	v_cvt_pk_bf16_f32 v145, v118, v17
	global_store_short v[150:151], v145, off offset:32 nt
	v_cvt_pk_bf16_f32 v145, v102, v17
	global_store_short v[150:151], v145, off offset:64 nt
	v_cvt_pk_bf16_f32 v145, v86, v17
	global_store_short v[150:151], v145, off offset:96 nt
	v_cvt_pk_bf16_f32 v145, v62, v17
	global_store_short v[150:151], v145, off offset:256 nt
	v_cvt_pk_bf16_f32 v145, v54, v17
	global_store_short v[150:151], v145, off offset:288 nt
	v_cvt_pk_bf16_f32 v145, v38, v17
	global_store_short v[150:151], v145, off offset:320 nt
	v_cvt_pk_bf16_f32 v145, v22, v17
	global_store_short v[150:151], v145, off offset:352 nt
	v_or_b32_e32 v150, 1, v144
	v_mov_b32_e32 v151, v17
	v_lshl_add_u64 v[150:151], s[50:51], 0, v[150:151]
	v_lshlrev_b64 v[150:151], s28, v[150:151]
	v_lshl_add_u64 v[150:151], v[150:151], 1, v[142:143]
	v_cvt_pk_bf16_f32 v145, v127, v17
	global_store_short v[150:151], v145, off nt
	v_cvt_pk_bf16_f32 v145, v119, v17
	global_store_short v[150:151], v145, off offset:32 nt
	v_cvt_pk_bf16_f32 v145, v103, v17
	global_store_short v[150:151], v145, off offset:64 nt
	v_cvt_pk_bf16_f32 v145, v87, v17
	global_store_short v[150:151], v145, off offset:96 nt
	v_cvt_pk_bf16_f32 v145, v63, v17
	global_store_short v[150:151], v145, off offset:256 nt
	v_cvt_pk_bf16_f32 v145, v55, v17
	global_store_short v[150:151], v145, off offset:288 nt
	v_cvt_pk_bf16_f32 v145, v39, v17
	global_store_short v[150:151], v145, off offset:320 nt
	v_cvt_pk_bf16_f32 v145, v23, v17
	global_store_short v[150:151], v145, off offset:352 nt
	v_or_b32_e32 v150, 2, v144
	v_mov_b32_e32 v151, v17
	v_lshl_add_u64 v[150:151], s[50:51], 0, v[150:151]
	v_lshlrev_b64 v[150:151], s28, v[150:151]
	v_lshl_add_u64 v[150:151], v[150:151], 1, v[142:143]
	v_cvt_pk_bf16_f32 v145, v128, v17
	global_store_short v[150:151], v145, off nt
	v_cvt_pk_bf16_f32 v145, v120, v17
	global_store_short v[150:151], v145, off offset:32 nt
	v_cvt_pk_bf16_f32 v145, v104, v17
	global_store_short v[150:151], v145, off offset:64 nt
	v_cvt_pk_bf16_f32 v145, v88, v17
	global_store_short v[150:151], v145, off offset:96 nt
	v_cvt_pk_bf16_f32 v145, v64, v17
	global_store_short v[150:151], v145, off offset:256 nt
	v_cvt_pk_bf16_f32 v145, v56, v17
	global_store_short v[150:151], v145, off offset:288 nt
	v_cvt_pk_bf16_f32 v145, v40, v17
	global_store_short v[150:151], v145, off offset:320 nt
	v_cvt_pk_bf16_f32 v145, v24, v17
	global_store_short v[150:151], v145, off offset:352 nt
	v_or_b32_e32 v150, 3, v144
	v_mov_b32_e32 v151, v17
	v_lshl_add_u64 v[150:151], s[50:51], 0, v[150:151]
	v_lshlrev_b64 v[150:151], s28, v[150:151]
	v_lshl_add_u64 v[150:151], v[150:151], 1, v[142:143]
	v_cvt_pk_bf16_f32 v145, v129, v17
	global_store_short v[150:151], v145, off nt
	v_cvt_pk_bf16_f32 v145, v121, v17
	global_store_short v[150:151], v145, off offset:32 nt
	v_cvt_pk_bf16_f32 v145, v105, v17
	global_store_short v[150:151], v145, off offset:64 nt
	v_cvt_pk_bf16_f32 v145, v89, v17
	global_store_short v[150:151], v145, off offset:96 nt
	v_cvt_pk_bf16_f32 v145, v65, v17
	global_store_short v[150:151], v145, off offset:256 nt
	v_cvt_pk_bf16_f32 v145, v57, v17
	global_store_short v[150:151], v145, off offset:288 nt
	v_cvt_pk_bf16_f32 v145, v41, v17
	global_store_short v[150:151], v145, off offset:320 nt
	v_cvt_pk_bf16_f32 v145, v25, v17
	global_store_short v[150:151], v145, off offset:352 nt
	v_or_b32_e32 v150, 4, v144
	v_mov_b32_e32 v151, v17
	v_lshl_add_u64 v[150:151], s[50:51], 0, v[150:151]
	v_lshlrev_b64 v[150:151], s28, v[150:151]
	v_lshl_add_u64 v[150:151], v[150:151], 1, v[142:143]
	v_cvt_pk_bf16_f32 v145, v122, v17
	global_store_short v[150:151], v145, off nt
	v_cvt_pk_bf16_f32 v145, v110, v17
	global_store_short v[150:151], v145, off offset:32 nt
	v_cvt_pk_bf16_f32 v145, v94, v17
	global_store_short v[150:151], v145, off offset:64 nt
	v_cvt_pk_bf16_f32 v145, v78, v17
	global_store_short v[150:151], v145, off offset:96 nt
	v_cvt_pk_bf16_f32 v145, v58, v17
	global_store_short v[150:151], v145, off offset:256 nt
	v_cvt_pk_bf16_f32 v145, v46, v17
	global_store_short v[150:151], v145, off offset:288 nt
	v_cvt_pk_bf16_f32 v145, v30, v17
	global_store_short v[150:151], v145, off offset:320 nt
	v_cvt_pk_bf16_f32 v145, v12, v17
	global_store_short v[150:151], v145, off offset:352 nt
	v_or_b32_e32 v150, 5, v144
	v_mov_b32_e32 v151, v17
	v_lshl_add_u64 v[150:151], s[50:51], 0, v[150:151]
	v_lshlrev_b64 v[150:151], s28, v[150:151]
	v_lshl_add_u64 v[150:151], v[150:151], 1, v[142:143]
	v_cvt_pk_bf16_f32 v145, v123, v17
	global_store_short v[150:151], v145, off nt
	v_cvt_pk_bf16_f32 v145, v111, v17
	global_store_short v[150:151], v145, off offset:32 nt
	v_cvt_pk_bf16_f32 v145, v95, v17
	global_store_short v[150:151], v145, off offset:64 nt
	v_cvt_pk_bf16_f32 v145, v79, v17
	global_store_short v[150:151], v145, off offset:96 nt
	v_cvt_pk_bf16_f32 v145, v59, v17
	global_store_short v[150:151], v145, off offset:256 nt
	v_cvt_pk_bf16_f32 v145, v47, v17
	global_store_short v[150:151], v145, off offset:288 nt
	v_cvt_pk_bf16_f32 v145, v31, v17
	global_store_short v[150:151], v145, off offset:320 nt
	v_cvt_pk_bf16_f32 v145, v13, v17
	global_store_short v[150:151], v145, off offset:352 nt
	v_or_b32_e32 v150, 6, v144
	v_mov_b32_e32 v151, v17
	v_lshl_add_u64 v[150:151], s[50:51], 0, v[150:151]
	v_lshlrev_b64 v[150:151], s28, v[150:151]
	v_lshl_add_u64 v[150:151], v[150:151], 1, v[142:143]
	v_cvt_pk_bf16_f32 v145, v124, v17
	global_store_short v[150:151], v145, off nt
	v_cvt_pk_bf16_f32 v145, v112, v17
	global_store_short v[150:151], v145, off offset:32 nt
	v_cvt_pk_bf16_f32 v145, v96, v17
	global_store_short v[150:151], v145, off offset:64 nt
	v_cvt_pk_bf16_f32 v145, v80, v17
	global_store_short v[150:151], v145, off offset:96 nt
	v_cvt_pk_bf16_f32 v145, v60, v17
	global_store_short v[150:151], v145, off offset:256 nt
	v_cvt_pk_bf16_f32 v145, v48, v17
	global_store_short v[150:151], v145, off offset:288 nt
	v_cvt_pk_bf16_f32 v145, v32, v17
	global_store_short v[150:151], v145, off offset:320 nt
	v_cvt_pk_bf16_f32 v145, v14, v17
	global_store_short v[150:151], v145, off offset:352 nt
	v_or_b32_e32 v150, 7, v144
	v_mov_b32_e32 v151, v17
	v_lshl_add_u64 v[150:151], s[50:51], 0, v[150:151]
	v_lshlrev_b64 v[150:151], s28, v[150:151]
	v_lshl_add_u64 v[150:151], v[150:151], 1, v[142:143]
	v_cvt_pk_bf16_f32 v145, v125, v17
	global_store_short v[150:151], v145, off nt
	v_cvt_pk_bf16_f32 v145, v113, v17
	global_store_short v[150:151], v145, off offset:32 nt
	v_cvt_pk_bf16_f32 v145, v97, v17
	global_store_short v[150:151], v145, off offset:64 nt
	v_cvt_pk_bf16_f32 v145, v81, v17
	global_store_short v[150:151], v145, off offset:96 nt
	v_cvt_pk_bf16_f32 v145, v61, v17
	global_store_short v[150:151], v145, off offset:256 nt
	v_cvt_pk_bf16_f32 v145, v49, v17
	global_store_short v[150:151], v145, off offset:288 nt
	v_cvt_pk_bf16_f32 v145, v33, v17
	global_store_short v[150:151], v145, off offset:320 nt
	v_cvt_pk_bf16_f32 v145, v15, v17
	global_store_short v[150:151], v145, off offset:352 nt
	v_or_b32_e32 v150, 0x80, v144
	v_mov_b32_e32 v151, v17
	v_lshl_add_u64 v[150:151], s[50:51], 0, v[150:151]
	v_lshlrev_b64 v[150:151], s28, v[150:151]
	v_lshl_add_u64 v[150:151], v[150:151], 1, v[142:143]
	v_cvt_pk_bf16_f32 v145, v114, v17
	global_store_short v[150:151], v145, off nt
	v_cvt_pk_bf16_f32 v145, v98, v17
	global_store_short v[150:151], v145, off offset:32 nt
	v_cvt_pk_bf16_f32 v145, v82, v17
	global_store_short v[150:151], v145, off offset:64 nt
	v_cvt_pk_bf16_f32 v145, v70, v17
	global_store_short v[150:151], v145, off offset:96 nt
	v_cvt_pk_bf16_f32 v145, v50, v17
	global_store_short v[150:151], v145, off offset:256 nt
	v_cvt_pk_bf16_f32 v145, v34, v17
	global_store_short v[150:151], v145, off offset:288 nt
	v_cvt_pk_bf16_f32 v145, v18, v17
	global_store_short v[150:151], v145, off offset:320 nt
	v_cvt_pk_bf16_f32 v145, v4, v17
	global_store_short v[150:151], v145, off offset:352 nt
	v_or_b32_e32 v150, 0x81, v144
	v_mov_b32_e32 v151, v17
	v_lshl_add_u64 v[150:151], s[50:51], 0, v[150:151]
	v_lshlrev_b64 v[150:151], s28, v[150:151]
	v_lshl_add_u64 v[150:151], v[150:151], 1, v[142:143]
	v_cvt_pk_bf16_f32 v145, v115, v17
	global_store_short v[150:151], v145, off nt
	v_cvt_pk_bf16_f32 v145, v99, v17
	global_store_short v[150:151], v145, off offset:32 nt
	v_cvt_pk_bf16_f32 v145, v83, v17
	global_store_short v[150:151], v145, off offset:64 nt
	v_cvt_pk_bf16_f32 v145, v71, v17
	global_store_short v[150:151], v145, off offset:96 nt
	v_cvt_pk_bf16_f32 v145, v51, v17
	global_store_short v[150:151], v145, off offset:256 nt
	v_cvt_pk_bf16_f32 v145, v35, v17
	global_store_short v[150:151], v145, off offset:288 nt
	v_cvt_pk_bf16_f32 v145, v19, v17
	global_store_short v[150:151], v145, off offset:320 nt
	v_cvt_pk_bf16_f32 v145, v5, v17
	global_store_short v[150:151], v145, off offset:352 nt
	v_or_b32_e32 v150, 0x82, v144
	v_mov_b32_e32 v151, v17
	v_lshl_add_u64 v[150:151], s[50:51], 0, v[150:151]
	v_lshlrev_b64 v[150:151], s28, v[150:151]
	v_lshl_add_u64 v[150:151], v[150:151], 1, v[142:143]
	v_cvt_pk_bf16_f32 v145, v116, v17
	global_store_short v[150:151], v145, off nt
	v_cvt_pk_bf16_f32 v145, v100, v17
	global_store_short v[150:151], v145, off offset:32 nt
	v_cvt_pk_bf16_f32 v145, v84, v17
	global_store_short v[150:151], v145, off offset:64 nt
	v_cvt_pk_bf16_f32 v145, v72, v17
	global_store_short v[150:151], v145, off offset:96 nt
	v_cvt_pk_bf16_f32 v145, v52, v17
	global_store_short v[150:151], v145, off offset:256 nt
	v_cvt_pk_bf16_f32 v145, v36, v17
	global_store_short v[150:151], v145, off offset:288 nt
	v_cvt_pk_bf16_f32 v145, v20, v17
	global_store_short v[150:151], v145, off offset:320 nt
	v_cvt_pk_bf16_f32 v145, v6, v17
	global_store_short v[150:151], v145, off offset:352 nt
	v_or_b32_e32 v150, 0x83, v144
	v_mov_b32_e32 v151, v17
	v_lshl_add_u64 v[150:151], s[50:51], 0, v[150:151]
	v_lshlrev_b64 v[150:151], s28, v[150:151]
	v_lshl_add_u64 v[150:151], v[150:151], 1, v[142:143]
	v_cvt_pk_bf16_f32 v145, v117, v17
	global_store_short v[150:151], v145, off nt
	v_cvt_pk_bf16_f32 v145, v101, v17
	global_store_short v[150:151], v145, off offset:32 nt
	v_cvt_pk_bf16_f32 v145, v85, v17
	global_store_short v[150:151], v145, off offset:64 nt
	v_cvt_pk_bf16_f32 v145, v73, v17
	global_store_short v[150:151], v145, off offset:96 nt
	v_cvt_pk_bf16_f32 v145, v53, v17
	global_store_short v[150:151], v145, off offset:256 nt
	v_cvt_pk_bf16_f32 v145, v37, v17
	global_store_short v[150:151], v145, off offset:288 nt
	v_cvt_pk_bf16_f32 v145, v21, v17
	global_store_short v[150:151], v145, off offset:320 nt
	v_cvt_pk_bf16_f32 v145, v7, v17
	global_store_short v[150:151], v145, off offset:352 nt
	v_or_b32_e32 v150, 0x84, v144
	v_mov_b32_e32 v151, v17
	v_lshl_add_u64 v[150:151], s[50:51], 0, v[150:151]
	v_lshlrev_b64 v[150:151], s28, v[150:151]
	v_lshl_add_u64 v[150:151], v[150:151], 1, v[142:143]
	v_cvt_pk_bf16_f32 v145, v106, v17
	global_store_short v[150:151], v145, off nt
	v_cvt_pk_bf16_f32 v145, v90, v17
	global_store_short v[150:151], v145, off offset:32 nt
	v_cvt_pk_bf16_f32 v145, v74, v17
	global_store_short v[150:151], v145, off offset:64 nt
	v_cvt_pk_bf16_f32 v145, v66, v17
	global_store_short v[150:151], v145, off offset:96 nt
	v_cvt_pk_bf16_f32 v145, v42, v17
	global_store_short v[150:151], v145, off offset:256 nt
	v_cvt_pk_bf16_f32 v145, v26, v17
	global_store_short v[150:151], v145, off offset:288 nt
	v_cvt_pk_bf16_f32 v145, v8, v17
	global_store_short v[150:151], v145, off offset:320 nt
	v_cvt_pk_bf16_f32 v145, v0, v17
	global_store_short v[150:151], v145, off offset:352 nt
	v_or_b32_e32 v150, 0x85, v144
	v_mov_b32_e32 v151, v17
	v_lshl_add_u64 v[150:151], s[50:51], 0, v[150:151]
	v_lshlrev_b64 v[150:151], s28, v[150:151]
	v_lshl_add_u64 v[150:151], v[150:151], 1, v[142:143]
	v_cvt_pk_bf16_f32 v145, v107, v17
	global_store_short v[150:151], v145, off nt
	v_cvt_pk_bf16_f32 v145, v91, v17
	global_store_short v[150:151], v145, off offset:32 nt
	v_cvt_pk_bf16_f32 v145, v75, v17
	global_store_short v[150:151], v145, off offset:64 nt
	v_cvt_pk_bf16_f32 v145, v67, v17
	global_store_short v[150:151], v145, off offset:96 nt
	v_cvt_pk_bf16_f32 v145, v43, v17
	global_store_short v[150:151], v145, off offset:256 nt
	v_cvt_pk_bf16_f32 v145, v27, v17
	global_store_short v[150:151], v145, off offset:288 nt
	v_cvt_pk_bf16_f32 v145, v9, v17
	global_store_short v[150:151], v145, off offset:320 nt
	v_cvt_pk_bf16_f32 v145, v1, v17
	global_store_short v[150:151], v145, off offset:352 nt
	v_or_b32_e32 v150, 0x86, v144
	v_mov_b32_e32 v151, v17
	v_lshl_add_u64 v[150:151], s[50:51], 0, v[150:151]
	v_lshlrev_b64 v[150:151], s28, v[150:151]
	v_lshl_add_u64 v[150:151], v[150:151], 1, v[142:143]
	v_cvt_pk_bf16_f32 v145, v108, v17
	global_store_short v[150:151], v145, off nt
	v_cvt_pk_bf16_f32 v145, v92, v17
	global_store_short v[150:151], v145, off offset:32 nt
	v_cvt_pk_bf16_f32 v145, v76, v17
	global_store_short v[150:151], v145, off offset:64 nt
	v_cvt_pk_bf16_f32 v145, v68, v17
	global_store_short v[150:151], v145, off offset:96 nt
	v_cvt_pk_bf16_f32 v145, v44, v17
	global_store_short v[150:151], v145, off offset:256 nt
	v_cvt_pk_bf16_f32 v145, v28, v17
	global_store_short v[150:151], v145, off offset:288 nt
	v_cvt_pk_bf16_f32 v145, v10, v17
	global_store_short v[150:151], v145, off offset:320 nt
	v_cvt_pk_bf16_f32 v145, v2, v17
	global_store_short v[150:151], v145, off offset:352 nt
	v_or_b32_e32 v144, 0x87, v144
	v_mov_b32_e32 v145, v17
	v_lshl_add_u64 v[144:145], s[50:51], 0, v[144:145]
	v_lshlrev_b64 v[144:145], s28, v[144:145]
	v_lshl_add_u64 v[142:143], v[144:145], 1, v[142:143]
	v_cvt_pk_bf16_f32 v144, v109, v17
	global_store_short v[142:143], v144, off nt
	v_cvt_pk_bf16_f32 v144, v93, v17
	global_store_short v[142:143], v144, off offset:32 nt
	v_cvt_pk_bf16_f32 v144, v77, v17
	global_store_short v[142:143], v144, off offset:64 nt
	v_cvt_pk_bf16_f32 v144, v69, v17
	global_store_short v[142:143], v144, off offset:96 nt
	v_cvt_pk_bf16_f32 v144, v45, v17
	global_store_short v[142:143], v144, off offset:256 nt
	v_cvt_pk_bf16_f32 v144, v29, v17
	global_store_short v[142:143], v144, off offset:288 nt
	v_cvt_pk_bf16_f32 v144, v11, v17
	global_store_short v[142:143], v144, off offset:320 nt
	v_cvt_pk_bf16_f32 v144, v3, v17
	global_store_short v[142:143], v144, off offset:352 nt
	s_mov_b64 s[92:93], 0x2000
	s_mov_b64 s[90:91], s[62:63]
	s_cbranch_execz .LBB0_220

.LBB0_652:
	v_lshl_add_u32 v146, s44, 8, v142
	v_lshl_or_b32 v140, s86, 8, v144
	v_ashrrev_i32_e32 v147, 31, v146
	v_ashrrev_i32_e32 v141, 31, v140
	v_lshlrev_b64 v[148:149], 14, v[146:147]
	v_lshl_add_u64 v[148:149], s[70:71], 0, v[148:149]
	v_lshlrev_b64 v[150:151], 1, v[140:141]
	v_lshl_add_u64 v[140:141], v[148:149], 0, v[150:151]
	v_cvt_pk_bf16_f32 v126, v126, v127
	v_cvt_pk_bf16_f32 v127, v128, v129
	v_cvt_pk_bf16_f32 v128, v122, v123
	v_cvt_pk_bf16_f32 v129, v124, v125
	global_store_dwordx4 v[140:141], v[126:129], off nt
	v_cvt_pk_bf16_f32 v114, v114, v115
	v_cvt_pk_bf16_f32 v115, v116, v117
	v_cvt_pk_bf16_f32 v116, v106, v107
	v_or_b32_e32 v106, 16, v146
	v_ashrrev_i32_e32 v107, 31, v106
	v_lshlrev_b64 v[106:107], 14, v[106:107]
	v_lshl_add_u64 v[106:107], s[70:71], 0, v[106:107]
	v_cvt_pk_bf16_f32 v117, v108, v109
	global_store_dwordx4 v[140:141], v[114:117], off offset:256 nt
	s_mov_b32 s19, 0x200000
	s_mov_b64 s[28:29], 0x200000
	v_lshl_add_u64 v[114:115], v[106:107], 0, v[150:151]
	v_cvt_pk_bf16_f32 v106, v118, v119
	v_cvt_pk_bf16_f32 v107, v120, v121
	v_cvt_pk_bf16_f32 v108, v110, v111
	v_cvt_pk_bf16_f32 v109, v112, v113
	global_store_dwordx4 v[114:115], v[106:109], off nt
	v_cvt_pk_bf16_f32 v98, v98, v99
	v_cvt_pk_bf16_f32 v99, v100, v101
	v_cvt_pk_bf16_f32 v100, v90, v91
	v_or_b32_e32 v90, 32, v146
	v_ashrrev_i32_e32 v91, 31, v90
	v_lshlrev_b64 v[90:91], 14, v[90:91]
	v_lshl_add_u64 v[90:91], s[70:71], 0, v[90:91]
	v_cvt_pk_bf16_f32 v101, v92, v93
	global_store_dwordx4 v[114:115], v[98:101], off offset:256 nt
	s_mov_b64 s[90:91], s[62:63]
	s_nop 0
	v_lshl_add_u64 v[98:99], v[90:91], 0, v[150:151]
	v_cvt_pk_bf16_f32 v90, v102, v103
	v_cvt_pk_bf16_f32 v91, v104, v105
	v_cvt_pk_bf16_f32 v92, v94, v95
	v_cvt_pk_bf16_f32 v93, v96, v97
	global_store_dwordx4 v[98:99], v[90:93], off nt
	v_cvt_pk_bf16_f32 v82, v82, v83
	v_cvt_pk_bf16_f32 v83, v84, v85
	v_cvt_pk_bf16_f32 v84, v74, v75
	v_or_b32_e32 v74, 48, v146
	v_ashrrev_i32_e32 v75, 31, v74
	v_lshlrev_b64 v[74:75], 14, v[74:75]
	v_lshl_add_u64 v[74:75], s[70:71], 0, v[74:75]
	v_cvt_pk_bf16_f32 v85, v76, v77
	global_store_dwordx4 v[98:99], v[82:85], off offset:256 nt
	s_nop 1
	v_lshl_add_u64 v[82:83], v[74:75], 0, v[150:151]
	v_cvt_pk_bf16_f32 v74, v86, v87
	v_cvt_pk_bf16_f32 v75, v88, v89
	v_cvt_pk_bf16_f32 v76, v78, v79
	v_cvt_pk_bf16_f32 v77, v80, v81
	global_store_dwordx4 v[82:83], v[74:77], off nt
	v_cvt_pk_bf16_f32 v70, v70, v71
	v_cvt_pk_bf16_f32 v71, v72, v73
	v_cvt_pk_bf16_f32 v72, v66, v67
	v_cvt_pk_bf16_f32 v73, v68, v69
	global_store_dwordx4 v[82:83], v[70:73], off offset:256 nt
	v_cvt_pk_bf16_f32 v62, v62, v63
	v_cvt_pk_bf16_f32 v63, v64, v65
	v_cvt_pk_bf16_f32 v64, v58, v59
	v_add_co_u32_e32 v58, vcc, s19, v140
	v_lshl_add_u64 v[66:67], v[140:141], 0, s[28:29]
	s_nop 0
	v_addc_co_u32_e32 v59, vcc, 0, v141, vcc
	s_mov_b32 s19, 0x240000
	v_cvt_pk_bf16_f32 v65, v60, v61
	global_store_dwordx4 v[58:59], v[62:65], off nt
	v_cvt_pk_bf16_f32 v50, v50, v51
	v_cvt_pk_bf16_f32 v51, v52, v53
	v_cvt_pk_bf16_f32 v52, v42, v43
	v_cvt_pk_bf16_f32 v53, v44, v45
	global_store_dwordx4 v[66:67], v[50:53], off offset:256 nt
	s_mov_b64 s[28:29], 0x240000
	v_cvt_pk_bf16_f32 v42, v54, v55
	v_cvt_pk_bf16_f32 v43, v56, v57
	v_cvt_pk_bf16_f32 v44, v46, v47
	v_add_co_u32_e32 v46, vcc, s19, v140
	v_lshl_add_u64 v[50:51], v[140:141], 0, s[28:29]
	s_nop 0
	v_addc_co_u32_e32 v47, vcc, 0, v141, vcc
	s_mov_b32 s19, 0x280000
	v_cvt_pk_bf16_f32 v45, v48, v49
	global_store_dwordx4 v[46:47], v[42:45], off nt
	v_cvt_pk_bf16_f32 v34, v34, v35
	v_cvt_pk_bf16_f32 v35, v36, v37
	v_cvt_pk_bf16_f32 v36, v26, v27
	v_cvt_pk_bf16_f32 v37, v28, v29
	global_store_dwordx4 v[50:51], v[34:37], off offset:256 nt
	s_mov_b64 s[28:29], 0x280000
	v_cvt_pk_bf16_f32 v26, v38, v39
	v_cvt_pk_bf16_f32 v27, v40, v41
	v_cvt_pk_bf16_f32 v28, v30, v31
	v_add_co_u32_e32 v30, vcc, s19, v140
	v_lshl_add_u64 v[34:35], v[140:141], 0, s[28:29]
	s_nop 0
	v_addc_co_u32_e32 v31, vcc, 0, v141, vcc
	s_mov_b32 s19, 0x2c0000
	v_cvt_pk_bf16_f32 v29, v32, v33
	global_store_dwordx4 v[30:31], v[26:29], off nt
	v_cvt_pk_bf16_f32 v18, v18, v19
	v_cvt_pk_bf16_f32 v19, v20, v21
	v_cvt_pk_bf16_f32 v20, v8, v9
	v_cvt_pk_bf16_f32 v21, v10, v11
	global_store_dwordx4 v[34:35], v[18:21], off offset:256 nt
	v_cvt_pk_bf16_f32 v8, v22, v23
	v_cvt_pk_bf16_f32 v9, v24, v25
	v_cvt_pk_bf16_f32 v10, v12, v13
	v_add_co_u32_e32 v12, vcc, s19, v140
	s_mov_b64 s[28:29], 0x2c0000
	s_nop 0
	v_addc_co_u32_e32 v13, vcc, 0, v141, vcc
	v_lshl_add_u64 v[18:19], v[140:141], 0, s[28:29]
	s_and_b64 vcc, exec, s[38:39]
	s_mov_b64 s[28:29], -1
	v_cvt_pk_bf16_f32 v11, v14, v15
	global_store_dwordx4 v[12:13], v[8:11], off nt
	v_cvt_pk_bf16_f32 v4, v4, v5
	v_cvt_pk_bf16_f32 v5, v6, v7
	v_cvt_pk_bf16_f32 v6, v0, v1
	v_cvt_pk_bf16_f32 v7, v2, v3
	global_store_dwordx4 v[18:19], v[4:7], off offset:256 nt
	s_cbranch_vccnz .LBB0_643
	s_andn2_b64 vcc, exec, s[0:1]
	s_cbranch_vccnz .LBB0_642
	s_barrier
	s_branch .LBB0_642

.LBB0_720:
	v_lshl_add_u32 v162, s42, 8, v223
	v_lshl_or_b32 v136, s83, 6, v225
	v_ashrrev_i32_e32 v163, 31, v162
	v_lshlrev_b64 v[138:139], 14, v[162:163]
	v_ashrrev_i32_e32 v137, 31, v136
	v_lshl_add_u64 v[138:139], s[70:71], 0, v[138:139]
	v_lshlrev_b64 v[148:149], 1, v[136:137]
	v_lshl_add_u64 v[136:137], v[138:139], 0, v[148:149]
	v_add_co_u32_e32 v138, vcc, 0x1000, v136
	s_mov_b32 s19, 0x200000
	s_nop 0
	v_addc_co_u32_e32 v139, vcc, 0, v137, vcc
	v_add_co_u32_e32 v140, vcc, 0x2000, v136
	s_nop 1
	v_addc_co_u32_e32 v141, vcc, 0, v137, vcc
	v_add_co_u32_e32 v142, vcc, 0x3000, v136
	s_nop 1
	v_addc_co_u32_e32 v143, vcc, 0, v137, vcc
	global_load_dwordx2 v[200:201], v[136:137], off
	global_load_dwordx2 v[202:203], v[138:139], off
	global_load_dwordx2 v[196:197], v[140:141], off
	global_load_dwordx2 v[198:199], v[142:143], off
	v_add_co_u32_e32 v138, vcc, s20, v136
	s_nop 1
	v_addc_co_u32_e32 v139, vcc, 0, v137, vcc
	v_add_co_u32_e32 v140, vcc, 0x41000, v136
	s_nop 1
	v_addc_co_u32_e32 v141, vcc, 0, v137, vcc
	v_add_co_u32_e32 v142, vcc, 0x42000, v136
	s_nop 1
	v_addc_co_u32_e32 v143, vcc, 0, v137, vcc
	v_add_co_u32_e32 v144, vcc, 0x43000, v136
	s_nop 1
	v_addc_co_u32_e32 v145, vcc, 0, v137, vcc
	global_load_dwordx2 v[192:193], v[138:139], off
	global_load_dwordx2 v[194:195], v[140:141], off
	global_load_dwordx2 v[188:189], v[142:143], off
	global_load_dwordx2 v[190:191], v[144:145], off
	v_add_co_u32_e32 v138, vcc, s64, v136
	s_nop 1
	v_addc_co_u32_e32 v139, vcc, 0, v137, vcc
	v_add_co_u32_e32 v140, vcc, 0x81000, v136
	s_nop 1
	v_addc_co_u32_e32 v141, vcc, 0, v137, vcc
	v_add_co_u32_e32 v142, vcc, 0x82000, v136
	s_nop 1
	v_addc_co_u32_e32 v143, vcc, 0, v137, vcc
	v_add_co_u32_e32 v144, vcc, 0x83000, v136
	s_nop 1
	v_addc_co_u32_e32 v145, vcc, 0, v137, vcc
	global_load_dwordx2 v[184:185], v[138:139], off
	global_load_dwordx2 v[186:187], v[140:141], off
	global_load_dwordx2 v[180:181], v[142:143], off
	global_load_dwordx2 v[182:183], v[144:145], off
	v_add_co_u32_e32 v138, vcc, s66, v136
	s_nop 1
	v_addc_co_u32_e32 v139, vcc, 0, v137, vcc
	v_add_co_u32_e32 v140, vcc, 0xc1000, v136
	s_nop 1
	v_addc_co_u32_e32 v141, vcc, 0, v137, vcc
	v_add_co_u32_e32 v142, vcc, 0xc2000, v136
	s_nop 1
	v_addc_co_u32_e32 v143, vcc, 0, v137, vcc
	v_add_co_u32_e32 v144, vcc, 0xc3000, v136
	s_nop 1
	v_addc_co_u32_e32 v145, vcc, 0, v137, vcc
	global_load_dwordx2 v[176:177], v[138:139], off
	global_load_dwordx2 v[178:179], v[140:141], off
	global_load_dwordx2 v[172:173], v[142:143], off
	global_load_dwordx2 v[174:175], v[144:145], off
	v_add_co_u32_e32 v138, vcc, s19, v136
	s_mov_b32 s19, 0x240000
	s_nop 0
	v_addc_co_u32_e32 v139, vcc, 0, v137, vcc
	v_add_co_u32_e32 v140, vcc, 0x201000, v136
	s_nop 1
	v_addc_co_u32_e32 v141, vcc, 0, v137, vcc
	v_add_co_u32_e32 v142, vcc, 0x202000, v136
	s_nop 1
	v_addc_co_u32_e32 v143, vcc, 0, v137, vcc
	v_add_co_u32_e32 v144, vcc, 0x203000, v136
	s_nop 1
	v_addc_co_u32_e32 v145, vcc, 0, v137, vcc
	global_load_dwordx2 v[168:169], v[138:139], off
	global_load_dwordx2 v[170:171], v[140:141], off
	global_load_dwordx2 v[164:165], v[142:143], off
	global_load_dwordx2 v[166:167], v[144:145], off
	v_add_co_u32_e32 v138, vcc, s19, v136
	s_mov_b32 s19, 0x280000
	s_nop 0
	v_addc_co_u32_e32 v139, vcc, 0, v137, vcc
	v_add_co_u32_e32 v140, vcc, 0x241000, v136
	s_nop 1
	v_addc_co_u32_e32 v141, vcc, 0, v137, vcc
	v_add_co_u32_e32 v142, vcc, 0x242000, v136
	s_nop 1
	v_addc_co_u32_e32 v143, vcc, 0, v137, vcc
	v_add_co_u32_e32 v144, vcc, 0x243000, v136
	s_nop 1
	v_addc_co_u32_e32 v145, vcc, 0, v137, vcc
	global_load_dwordx2 v[158:159], v[138:139], off
	global_load_dwordx2 v[160:161], v[140:141], off
	global_load_dwordx2 v[154:155], v[142:143], off
	global_load_dwordx2 v[156:157], v[144:145], off
	v_add_co_u32_e32 v138, vcc, s19, v136
	s_mov_b32 s19, 0x2c0000
	s_nop 0
	v_addc_co_u32_e32 v139, vcc, 0, v137, vcc
	v_add_co_u32_e32 v140, vcc, 0x281000, v136
	s_nop 1
	v_addc_co_u32_e32 v141, vcc, 0, v137, vcc
	v_add_co_u32_e32 v142, vcc, 0x282000, v136
	s_nop 1
	v_addc_co_u32_e32 v143, vcc, 0, v137, vcc
	v_add_co_u32_e32 v146, vcc, 0x283000, v136
	s_nop 1
	v_addc_co_u32_e32 v147, vcc, 0, v137, vcc
	global_load_dwordx2 v[150:151], v[138:139], off
	global_load_dwordx2 v[152:153], v[140:141], off
	global_load_dwordx2 v[144:145], v[142:143], off
	s_nop 0
	global_load_dwordx2 v[146:147], v[146:147], off
	v_add_co_u32_e32 v138, vcc, s19, v136
	s_nop 1
	v_addc_co_u32_e32 v139, vcc, 0, v137, vcc
	v_add_co_u32_e32 v142, vcc, 0x2c1000, v136
	s_nop 1
	v_addc_co_u32_e32 v143, vcc, 0, v137, vcc
	v_add_co_u32_e32 v204, vcc, 0x2c2000, v136
	s_nop 1
	v_addc_co_u32_e32 v205, vcc, 0, v137, vcc
	v_add_co_u32_e32 v206, vcc, 0x2c3000, v136
	s_nop 1
	v_addc_co_u32_e32 v207, vcc, 0, v137, vcc
	global_load_dwordx2 v[140:141], v[138:139], off
	s_nop 0
	global_load_dwordx2 v[142:143], v[142:143], off
	s_nop 0
	global_load_dwordx2 v[136:137], v[204:205], off
	global_load_dwordx2 v[138:139], v[206:207], off
	v_mul_f32_e32 v126, 0xbfb8aa3b, v126
	v_mul_f32_e32 v122, 0xbfb8aa3b, v122
	v_exp_f32_e32 v126, v126
	v_exp_f32_e32 v122, v122
	v_mul_f32_e32 v123, 0xbfb8aa3b, v123
	v_exp_f32_e32 v123, v123
	v_add_f32_e32 v126, 1.0, v126
	v_add_f32_e32 v122, 1.0, v122
	v_rcp_f32_e32 v206, v126
	v_mul_f32_e32 v126, 0xbfb8aa3b, v128
	v_rcp_f32_e32 v207, v122
	v_add_f32_e32 v122, 1.0, v123
	v_mul_f32_e32 v123, 0xbfb8aa3b, v124
	v_mul_f32_e32 v118, 0xbfb8aa3b, v118
	v_mul_f32_e32 v114, 0xbfb8aa3b, v114
	v_exp_f32_e32 v126, v126
	v_mul_f32_e32 v128, 0xbfb8aa3b, v129
	v_exp_f32_e32 v123, v123
	v_mul_f32_e32 v124, 0xbfb8aa3b, v125
	v_exp_f32_e32 v118, v118
	v_mul_f32_e32 v119, 0xbfb8aa3b, v119
	v_exp_f32_e32 v114, v114
	v_mul_f32_e32 v115, 0xbfb8aa3b, v115
	v_exp_f32_e32 v129, v128
	v_exp_f32_e32 v124, v124
	v_exp_f32_e32 v119, v119
	v_exp_f32_e32 v115, v115
	v_mul_f32_e32 v127, 0xbfb8aa3b, v127
	v_add_f32_e32 v126, 1.0, v126
	v_rcp_f32_e32 v205, v122
	v_add_f32_e32 v122, 1.0, v123
	v_add_f32_e32 v118, 1.0, v118
	v_add_f32_e32 v114, 1.0, v114
	v_exp_f32_e32 v127, v127
	v_rcp_f32_e32 v128, v126
	v_add_f32_e32 v126, 1.0, v129
	v_rcp_f32_e32 v129, v122
	v_add_f32_e32 v122, 1.0, v124
	v_rcp_f32_e32 v124, v118
	v_add_f32_e32 v118, 1.0, v119
	v_mul_f32_e32 v119, 0xbfb8aa3b, v120
	v_rcp_f32_e32 v125, v114
	v_add_f32_e32 v114, 1.0, v115
	v_mul_f32_e32 v115, 0xbfb8aa3b, v116
	v_mul_f32_e32 v110, 0xbfb8aa3b, v110
	v_mul_f32_e32 v106, 0xbfb8aa3b, v106
	v_exp_f32_e32 v119, v119
	v_mul_f32_e32 v120, 0xbfb8aa3b, v121
	v_exp_f32_e32 v115, v115
	v_mul_f32_e32 v116, 0xbfb8aa3b, v117
	v_exp_f32_e32 v110, v110
	v_mul_f32_e32 v111, 0xbfb8aa3b, v111
	v_exp_f32_e32 v106, v106
	v_mul_f32_e32 v107, 0xbfb8aa3b, v107
	v_exp_f32_e32 v121, v120
	v_exp_f32_e32 v116, v116
	v_exp_f32_e32 v111, v111
	v_exp_f32_e32 v107, v107
	v_add_f32_e32 v127, 1.0, v127
	v_rcp_f32_e32 v204, v127
	v_rcp_f32_e32 v127, v122
	v_rcp_f32_e32 v122, v118
	v_add_f32_e32 v118, 1.0, v119
	v_rcp_f32_e32 v123, v114
	v_add_f32_e32 v114, 1.0, v115
	v_add_f32_e32 v110, 1.0, v110
	v_add_f32_e32 v106, 1.0, v106
	v_rcp_f32_e32 v120, v118
	v_add_f32_e32 v118, 1.0, v121
	v_rcp_f32_e32 v121, v114
	v_add_f32_e32 v114, 1.0, v116
	v_rcp_f32_e32 v116, v110
	v_add_f32_e32 v110, 1.0, v111
	v_mul_f32_e32 v111, 0xbfb8aa3b, v112
	v_rcp_f32_e32 v117, v106
	v_add_f32_e32 v106, 1.0, v107
	v_mul_f32_e32 v107, 0xbfb8aa3b, v108
	v_exp_f32_e32 v111, v111
	v_mul_f32_e32 v112, 0xbfb8aa3b, v113
	v_exp_f32_e32 v107, v107
	v_mul_f32_e32 v108, 0xbfb8aa3b, v109
	v_mul_f32_e32 v102, 0xbfb8aa3b, v102
	v_exp_f32_e32 v113, v112
	v_exp_f32_e32 v108, v108
	v_exp_f32_e32 v102, v102
	v_mul_f32_e32 v103, 0xbfb8aa3b, v103
	v_exp_f32_e32 v103, v103
	v_rcp_f32_e32 v119, v114
	v_rcp_f32_e32 v114, v110
	v_add_f32_e32 v110, 1.0, v111
	v_rcp_f32_e32 v115, v106
	v_add_f32_e32 v106, 1.0, v107
	v_rcp_f32_e32 v112, v110
	v_add_f32_e32 v110, 1.0, v113
	v_rcp_f32_e32 v113, v106
	v_add_f32_e32 v106, 1.0, v108
	v_add_f32_e32 v102, 1.0, v102
	v_rcp_f32_e32 v111, v106
	v_rcp_f32_e32 v106, v102
	v_add_f32_e32 v102, 1.0, v103
	v_mul_f32_e32 v103, 0xbfb8aa3b, v104
	v_mul_f32_e32 v104, 0xbfb8aa3b, v105
	v_exp_f32_e32 v103, v103
	v_exp_f32_e32 v105, v104
	v_mul_f32_e32 v94, 0xbfb8aa3b, v94
	v_mul_f32_e32 v90, 0xbfb8aa3b, v90
	v_exp_f32_e32 v94, v94
	v_mul_f32_e32 v95, 0xbfb8aa3b, v95
	v_exp_f32_e32 v90, v90
	v_mul_f32_e32 v91, 0xbfb8aa3b, v91
	v_exp_f32_e32 v95, v95
	v_exp_f32_e32 v91, v91
	v_mul_f32_e32 v98, 0xbfb8aa3b, v98
	v_rcp_f32_e32 v104, v102
	v_add_f32_e32 v102, 1.0, v103
	v_add_f32_e32 v103, 1.0, v105
	v_exp_f32_e32 v105, v98
	v_mul_f32_e32 v98, 0xbfb8aa3b, v99
	v_exp_f32_e32 v99, v98
	v_mul_f32_e32 v100, 0xbfb8aa3b, v100
	v_add_f32_e32 v94, 1.0, v94
	v_add_f32_e32 v90, 1.0, v90
	v_exp_f32_e32 v100, v100
	v_mul_f32_e32 v101, 0xbfb8aa3b, v101
	v_rcp_f32_e32 v108, v94
	v_add_f32_e32 v94, 1.0, v95
	v_mul_f32_e32 v95, 0xbfb8aa3b, v96
	v_rcp_f32_e32 v109, v90
	v_add_f32_e32 v90, 1.0, v91
	v_mul_f32_e32 v91, 0xbfb8aa3b, v92
	v_mul_f32_e32 v86, 0xbfb8aa3b, v86
	v_mul_f32_e32 v82, 0xbfb8aa3b, v82
	v_exp_f32_e32 v101, v101
	v_exp_f32_e32 v95, v95
	v_mul_f32_e32 v96, 0xbfb8aa3b, v97
	v_exp_f32_e32 v91, v91
	v_mul_f32_e32 v92, 0xbfb8aa3b, v93
	v_exp_f32_e32 v86, v86
	v_mul_f32_e32 v87, 0xbfb8aa3b, v87
	v_exp_f32_e32 v82, v82
	v_mul_f32_e32 v83, 0xbfb8aa3b, v83
	v_exp_f32_e32 v97, v96
	v_exp_f32_e32 v92, v92
	v_exp_f32_e32 v87, v87
	v_exp_f32_e32 v83, v83
	v_add_f32_e32 v99, 1.0, v99
	v_rcp_f32_e32 v98, v103
	v_add_f32_e32 v103, 1.0, v105
	v_rcp_f32_e32 v105, v99
	v_add_f32_e32 v99, 1.0, v100
	v_rcp_f32_e32 v107, v103
	v_rcp_f32_e32 v103, v99
	v_add_f32_e32 v99, 1.0, v101
	v_rcp_f32_e32 v100, v94
	v_add_f32_e32 v94, 1.0, v95
	v_rcp_f32_e32 v101, v90
	v_add_f32_e32 v90, 1.0, v91
	v_add_f32_e32 v86, 1.0, v86
	v_add_f32_e32 v82, 1.0, v82
	v_rcp_f32_e32 v96, v94
	v_add_f32_e32 v94, 1.0, v97
	v_rcp_f32_e32 v97, v90
	v_add_f32_e32 v90, 1.0, v92
	v_rcp_f32_e32 v92, v86
	v_add_f32_e32 v86, 1.0, v87
	v_mul_f32_e32 v87, 0xbfb8aa3b, v88
	v_rcp_f32_e32 v93, v82
	v_add_f32_e32 v82, 1.0, v83
	v_mul_f32_e32 v83, 0xbfb8aa3b, v84
	v_mul_f32_e32 v78, 0xbfb8aa3b, v78
	v_mul_f32_e32 v74, 0xbfb8aa3b, v74
	v_exp_f32_e32 v87, v87
	v_mul_f32_e32 v88, 0xbfb8aa3b, v89
	v_exp_f32_e32 v83, v83
	v_mul_f32_e32 v84, 0xbfb8aa3b, v85
	v_exp_f32_e32 v78, v78
	v_mul_f32_e32 v79, 0xbfb8aa3b, v79
	v_exp_f32_e32 v74, v74
	v_mul_f32_e32 v75, 0xbfb8aa3b, v75
	v_exp_f32_e32 v89, v88
	v_exp_f32_e32 v84, v84
	v_exp_f32_e32 v79, v79
	v_exp_f32_e32 v75, v75
	v_rcp_f32_e32 v95, v90
	v_rcp_f32_e32 v90, v86
	v_add_f32_e32 v86, 1.0, v87
	v_rcp_f32_e32 v91, v82
	v_add_f32_e32 v82, 1.0, v83
	v_add_f32_e32 v78, 1.0, v78
	v_add_f32_e32 v74, 1.0, v74
	v_rcp_f32_e32 v88, v86
	v_add_f32_e32 v86, 1.0, v89
	v_rcp_f32_e32 v89, v82
	v_add_f32_e32 v82, 1.0, v84
	v_rcp_f32_e32 v84, v78
	v_add_f32_e32 v78, 1.0, v79
	v_mul_f32_e32 v79, 0xbfb8aa3b, v80
	v_rcp_f32_e32 v85, v74
	v_add_f32_e32 v74, 1.0, v75
	v_mul_f32_e32 v75, 0xbfb8aa3b, v76
	v_mul_f32_e32 v70, 0xbfb8aa3b, v70
	v_exp_f32_e32 v79, v79
	v_mul_f32_e32 v80, 0xbfb8aa3b, v81
	v_exp_f32_e32 v75, v75
	v_mul_f32_e32 v76, 0xbfb8aa3b, v77
	v_exp_f32_e32 v70, v70
	v_mul_f32_e32 v71, 0xbfb8aa3b, v71
	v_exp_f32_e32 v81, v80
	v_exp_f32_e32 v76, v76
	v_exp_f32_e32 v71, v71
	v_rcp_f32_e32 v87, v82
	v_rcp_f32_e32 v82, v78
	v_add_f32_e32 v78, 1.0, v79
	v_rcp_f32_e32 v83, v74
	v_add_f32_e32 v74, 1.0, v75
	v_add_f32_e32 v70, 1.0, v70
	v_rcp_f32_e32 v80, v78
	v_add_f32_e32 v78, 1.0, v81
	v_rcp_f32_e32 v81, v74
	v_add_f32_e32 v74, 1.0, v76
	v_rcp_f32_e32 v76, v70
	v_add_f32_e32 v70, 1.0, v71
	v_mul_f32_e32 v71, 0xbfb8aa3b, v72
	v_mul_f32_e32 v72, 0xbfb8aa3b, v73
	v_exp_f32_e32 v71, v71
	v_exp_f32_e32 v72, v72
	v_mul_f32_e32 v62, 0xbfb8aa3b, v62
	v_mul_f32_e32 v58, 0xbfb8aa3b, v58
	v_mul_f32_e32 v66, 0xbfb8aa3b, v66
	v_exp_f32_e32 v62, v62
	v_mul_f32_e32 v63, 0xbfb8aa3b, v63
	v_exp_f32_e32 v58, v58
	v_mul_f32_e32 v59, 0xbfb8aa3b, v59
	v_rcp_f32_e32 v79, v74
	v_rcp_f32_e32 v74, v70
	v_add_f32_e32 v70, 1.0, v71
	v_add_f32_e32 v71, 1.0, v72
	v_exp_f32_e32 v72, v66
	v_exp_f32_e32 v63, v63
	v_exp_f32_e32 v59, v59
	v_mul_f32_e32 v66, 0xbfb8aa3b, v67
	v_exp_f32_e32 v67, v66
	v_mul_f32_e32 v68, 0xbfb8aa3b, v68
	v_add_f32_e32 v62, 1.0, v62
	v_add_f32_e32 v58, 1.0, v58
	v_rcp_f32_e32 v66, v71
	v_add_f32_e32 v71, 1.0, v72
	v_exp_f32_e32 v68, v68
	v_mul_f32_e32 v69, 0xbfb8aa3b, v69
	v_rcp_f32_e32 v72, v62
	v_add_f32_e32 v62, 1.0, v63
	v_mul_f32_e32 v63, 0xbfb8aa3b, v64
	v_rcp_f32_e32 v73, v58
	v_add_f32_e32 v58, 1.0, v59
	v_mul_f32_e32 v59, 0xbfb8aa3b, v60
	v_mul_f32_e32 v54, 0xbfb8aa3b, v54
	v_mul_f32_e32 v50, 0xbfb8aa3b, v50
	v_exp_f32_e32 v69, v69
	v_exp_f32_e32 v63, v63
	v_mul_f32_e32 v64, 0xbfb8aa3b, v65
	v_exp_f32_e32 v59, v59
	v_mul_f32_e32 v60, 0xbfb8aa3b, v61
	v_exp_f32_e32 v54, v54
	v_mul_f32_e32 v55, 0xbfb8aa3b, v55
	v_exp_f32_e32 v50, v50
	v_mul_f32_e32 v51, 0xbfb8aa3b, v51
	v_exp_f32_e32 v65, v64
	v_exp_f32_e32 v60, v60
	v_exp_f32_e32 v55, v55
	v_exp_f32_e32 v51, v51
	v_add_f32_e32 v67, 1.0, v67
	v_rcp_f32_e32 v75, v67
	v_add_f32_e32 v67, 1.0, v68
	v_rcp_f32_e32 v77, v71
	v_rcp_f32_e32 v71, v67
	v_add_f32_e32 v67, 1.0, v69
	v_rcp_f32_e32 v68, v62
	v_add_f32_e32 v62, 1.0, v63
	v_rcp_f32_e32 v69, v58
	v_add_f32_e32 v58, 1.0, v59
	v_add_f32_e32 v54, 1.0, v54
	v_add_f32_e32 v50, 1.0, v50
	v_rcp_f32_e32 v64, v62
	v_add_f32_e32 v62, 1.0, v65
	v_rcp_f32_e32 v65, v58
	v_add_f32_e32 v58, 1.0, v60
	v_rcp_f32_e32 v60, v54
	v_add_f32_e32 v54, 1.0, v55
	v_mul_f32_e32 v55, 0xbfb8aa3b, v56
	v_rcp_f32_e32 v61, v50
	v_add_f32_e32 v50, 1.0, v51
	v_mul_f32_e32 v51, 0xbfb8aa3b, v52
	v_mul_f32_e32 v46, 0xbfb8aa3b, v46
	v_mul_f32_e32 v42, 0xbfb8aa3b, v42
	v_exp_f32_e32 v55, v55
	v_mul_f32_e32 v56, 0xbfb8aa3b, v57
	v_exp_f32_e32 v51, v51
	v_mul_f32_e32 v52, 0xbfb8aa3b, v53
	v_exp_f32_e32 v46, v46
	v_mul_f32_e32 v47, 0xbfb8aa3b, v47
	v_exp_f32_e32 v42, v42
	v_mul_f32_e32 v43, 0xbfb8aa3b, v43
	v_exp_f32_e32 v57, v56
	v_exp_f32_e32 v52, v52
	v_exp_f32_e32 v47, v47
	v_exp_f32_e32 v43, v43
	v_rcp_f32_e32 v63, v58
	v_rcp_f32_e32 v58, v54
	v_add_f32_e32 v54, 1.0, v55
	v_rcp_f32_e32 v59, v50
	v_add_f32_e32 v50, 1.0, v51
	v_add_f32_e32 v46, 1.0, v46
	v_add_f32_e32 v42, 1.0, v42
	v_rcp_f32_e32 v56, v54
	v_add_f32_e32 v54, 1.0, v57
	v_rcp_f32_e32 v57, v50
	v_add_f32_e32 v50, 1.0, v52
	v_rcp_f32_e32 v52, v46
	v_add_f32_e32 v46, 1.0, v47
	v_mul_f32_e32 v47, 0xbfb8aa3b, v48
	v_rcp_f32_e32 v53, v42
	v_add_f32_e32 v42, 1.0, v43
	v_mul_f32_e32 v43, 0xbfb8aa3b, v44
	v_exp_f32_e32 v47, v47
	v_mul_f32_e32 v48, 0xbfb8aa3b, v49
	v_exp_f32_e32 v43, v43
	v_mul_f32_e32 v44, 0xbfb8aa3b, v45
	v_mul_f32_e32 v38, 0xbfb8aa3b, v38
	v_exp_f32_e32 v49, v48
	v_exp_f32_e32 v44, v44
	v_exp_f32_e32 v38, v38
	v_mul_f32_e32 v39, 0xbfb8aa3b, v39
	v_exp_f32_e32 v39, v39
	v_rcp_f32_e32 v55, v50
	v_rcp_f32_e32 v50, v46
	v_add_f32_e32 v46, 1.0, v47
	v_rcp_f32_e32 v51, v42
	v_add_f32_e32 v42, 1.0, v43
	v_rcp_f32_e32 v48, v46
	v_add_f32_e32 v46, 1.0, v49
	v_rcp_f32_e32 v49, v42
	v_add_f32_e32 v42, 1.0, v44
	v_add_f32_e32 v38, 1.0, v38
	v_rcp_f32_e32 v47, v42
	v_rcp_f32_e32 v42, v38
	v_add_f32_e32 v38, 1.0, v39
	v_mul_f32_e32 v39, 0xbfb8aa3b, v40
	v_mul_f32_e32 v40, 0xbfb8aa3b, v41
	v_exp_f32_e32 v39, v39
	v_exp_f32_e32 v41, v40
	v_mul_f32_e32 v30, 0xbfb8aa3b, v30
	v_mul_f32_e32 v26, 0xbfb8aa3b, v26
	v_exp_f32_e32 v30, v30
	v_mul_f32_e32 v31, 0xbfb8aa3b, v31
	v_exp_f32_e32 v26, v26
	v_mul_f32_e32 v27, 0xbfb8aa3b, v27
	v_exp_f32_e32 v31, v31
	v_exp_f32_e32 v27, v27
	v_mul_f32_e32 v34, 0xbfb8aa3b, v34
	v_rcp_f32_e32 v40, v38
	v_add_f32_e32 v38, 1.0, v39
	v_add_f32_e32 v39, 1.0, v41
	v_exp_f32_e32 v41, v34
	v_mul_f32_e32 v34, 0xbfb8aa3b, v35
	v_exp_f32_e32 v35, v34
	v_mul_f32_e32 v36, 0xbfb8aa3b, v36
	v_add_f32_e32 v30, 1.0, v30
	v_add_f32_e32 v26, 1.0, v26
	v_exp_f32_e32 v36, v36
	v_mul_f32_e32 v37, 0xbfb8aa3b, v37
	v_rcp_f32_e32 v44, v30
	v_add_f32_e32 v30, 1.0, v31
	v_mul_f32_e32 v31, 0xbfb8aa3b, v32
	v_rcp_f32_e32 v45, v26
	v_add_f32_e32 v26, 1.0, v27
	v_mul_f32_e32 v27, 0xbfb8aa3b, v28
	v_mul_f32_e32 v22, 0xbfb8aa3b, v22
	v_mul_f32_e32 v18, 0xbfb8aa3b, v18
	v_exp_f32_e32 v37, v37
	v_exp_f32_e32 v31, v31
	v_mul_f32_e32 v32, 0xbfb8aa3b, v33
	v_exp_f32_e32 v27, v27
	v_mul_f32_e32 v28, 0xbfb8aa3b, v29
	v_exp_f32_e32 v22, v22
	v_mul_f32_e32 v23, 0xbfb8aa3b, v23
	v_exp_f32_e32 v18, v18
	v_mul_f32_e32 v19, 0xbfb8aa3b, v19
	v_exp_f32_e32 v33, v32
	v_exp_f32_e32 v28, v28
	v_exp_f32_e32 v23, v23
	v_exp_f32_e32 v19, v19
	v_add_f32_e32 v35, 1.0, v35
	v_rcp_f32_e32 v34, v39
	v_add_f32_e32 v39, 1.0, v41
	v_rcp_f32_e32 v41, v35
	v_add_f32_e32 v35, 1.0, v36
	v_rcp_f32_e32 v43, v39
	v_rcp_f32_e32 v39, v35
	v_add_f32_e32 v35, 1.0, v37
	v_rcp_f32_e32 v36, v30
	v_add_f32_e32 v30, 1.0, v31
	v_rcp_f32_e32 v37, v26
	v_add_f32_e32 v26, 1.0, v27
	v_add_f32_e32 v22, 1.0, v22
	v_add_f32_e32 v18, 1.0, v18
	v_rcp_f32_e32 v32, v30
	v_add_f32_e32 v30, 1.0, v33
	v_rcp_f32_e32 v33, v26
	v_add_f32_e32 v26, 1.0, v28
	v_rcp_f32_e32 v28, v22
	v_add_f32_e32 v22, 1.0, v23
	v_mul_f32_e32 v23, 0xbfb8aa3b, v24
	v_rcp_f32_e32 v29, v18
	v_add_f32_e32 v18, 1.0, v19
	v_mul_f32_e32 v19, 0xbfb8aa3b, v20
	v_mul_f32_e32 v12, 0xbfb8aa3b, v12
	v_mul_f32_e32 v8, 0xbfb8aa3b, v8
	v_exp_f32_e32 v23, v23
	v_mul_f32_e32 v24, 0xbfb8aa3b, v25
	v_exp_f32_e32 v19, v19
	v_mul_f32_e32 v20, 0xbfb8aa3b, v21
	v_exp_f32_e32 v12, v12
	v_mul_f32_e32 v13, 0xbfb8aa3b, v13
	v_exp_f32_e32 v8, v8
	v_mul_f32_e32 v9, 0xbfb8aa3b, v9
	v_exp_f32_e32 v25, v24
	v_exp_f32_e32 v20, v20
	v_exp_f32_e32 v13, v13
	v_exp_f32_e32 v9, v9
	v_rcp_f32_e32 v31, v26
	v_rcp_f32_e32 v26, v22
	v_add_f32_e32 v22, 1.0, v23
	v_rcp_f32_e32 v27, v18
	v_add_f32_e32 v18, 1.0, v19
	v_add_f32_e32 v12, 1.0, v12
	v_add_f32_e32 v8, 1.0, v8
	v_rcp_f32_e32 v24, v22
	v_add_f32_e32 v22, 1.0, v25
	v_rcp_f32_e32 v25, v18
	v_add_f32_e32 v18, 1.0, v20
	v_rcp_f32_e32 v20, v12
	v_add_f32_e32 v12, 1.0, v13
	v_mul_f32_e32 v13, 0xbfb8aa3b, v14
	v_rcp_f32_e32 v21, v8
	v_add_f32_e32 v8, 1.0, v9
	v_mul_f32_e32 v9, 0xbfb8aa3b, v10
	v_exp_f32_e32 v13, v13
	v_mul_f32_e32 v14, 0xbfb8aa3b, v15
	v_exp_f32_e32 v9, v9
	v_mul_f32_e32 v10, 0xbfb8aa3b, v11
	v_mul_f32_e32 v4, 0xbfb8aa3b, v4
	v_exp_f32_e32 v15, v14
	v_exp_f32_e32 v10, v10
	v_exp_f32_e32 v4, v4
	v_mul_f32_e32 v5, 0xbfb8aa3b, v5
	v_exp_f32_e32 v5, v5
	v_rcp_f32_e32 v23, v18
	v_rcp_f32_e32 v18, v12
	v_add_f32_e32 v12, 1.0, v13
	v_rcp_f32_e32 v19, v8
	v_add_f32_e32 v8, 1.0, v9
	v_rcp_f32_e32 v14, v12
	v_add_f32_e32 v12, 1.0, v15
	v_rcp_f32_e32 v15, v8
	v_add_f32_e32 v8, 1.0, v10
	v_add_f32_e32 v4, 1.0, v4
	v_rcp_f32_e32 v13, v8
	v_rcp_f32_e32 v8, v4
	v_add_f32_e32 v4, 1.0, v5
	v_mul_f32_e32 v5, 0xbfb8aa3b, v6
	v_mul_f32_e32 v6, 0xbfb8aa3b, v7
	v_exp_f32_e32 v5, v5
	v_exp_f32_e32 v7, v6
	v_mul_f32_e32 v0, 0xbfb8aa3b, v0
	v_rcp_f32_e32 v6, v4
	v_add_f32_e32 v4, 1.0, v5
	v_add_f32_e32 v5, 1.0, v7
	v_exp_f32_e32 v7, v0
	v_mul_f32_e32 v0, 0xbfb8aa3b, v1
	v_exp_f32_e32 v1, v0
	v_mul_f32_e32 v2, 0xbfb8aa3b, v2
	v_exp_f32_e32 v2, v2
	v_mul_f32_e32 v3, 0xbfb8aa3b, v3
	v_exp_f32_e32 v3, v3
	v_add_f32_e32 v1, 1.0, v1
	v_rcp_f32_e32 v0, v5
	v_add_f32_e32 v5, 1.0, v7
	v_rcp_f32_e32 v7, v1
	v_add_f32_e32 v1, 1.0, v2
	v_rcp_f32_e32 v9, v5
	v_rcp_f32_e32 v5, v1
	v_add_f32_e32 v1, 1.0, v3
	v_rcp_f32_e32 v126, v126
	v_rcp_f32_e32 v118, v118
	v_rcp_f32_e32 v110, v110
	v_rcp_f32_e32 v102, v102
	v_rcp_f32_e32 v99, v99
	v_rcp_f32_e32 v94, v94
	v_rcp_f32_e32 v86, v86
	v_rcp_f32_e32 v78, v78
	v_rcp_f32_e32 v70, v70
	v_rcp_f32_e32 v67, v67
	v_rcp_f32_e32 v62, v62
	v_rcp_f32_e32 v54, v54
	v_rcp_f32_e32 v46, v46
	v_rcp_f32_e32 v38, v38
	v_rcp_f32_e32 v35, v35
	v_rcp_f32_e32 v30, v30
	v_rcp_f32_e32 v22, v22
	v_rcp_f32_e32 v12, v12
	v_rcp_f32_e32 v4, v4
	v_rcp_f32_e32 v1, v1
	s_waitcnt vmcnt(0)
	v_lshlrev_b32_e32 v3, 16, v202
	v_lshlrev_b32_e32 v2, 16, v200
	v_pk_mul_f32 v[2:3], v[206:207], v[2:3]
	s_mov_b64 s[28:29], -1
	v_add_f32_e32 v2, 0, v2
	v_add_f32_e32 v10, v2, v3
	v_and_b32_e32 v3, 0xffff0000, v202
	v_and_b32_e32 v2, 0xffff0000, v200
	v_pk_mul_f32 v[2:3], v[204:205], v[2:3]
	s_mov_b64 s[92:93], 0x2000
	v_add_f32_e32 v2, 0, v2
	v_add_f32_e32 v11, v2, v3
	v_lshlrev_b32_e32 v3, 16, v203
	v_lshlrev_b32_e32 v2, 16, v201
	v_pk_mul_f32 v[2:3], v[128:129], v[2:3]
	s_mov_b64 s[90:91], s[62:63]
	v_add_f32_e32 v2, 0, v2
	v_add_f32_e32 v128, v2, v3
	v_and_b32_e32 v3, 0xffff0000, v203
	v_and_b32_e32 v2, 0xffff0000, v201
	v_pk_mul_f32 v[2:3], v[126:127], v[2:3]
	s_nop 0
	v_add_f32_e32 v2, 0, v2
	v_add_f32_e32 v126, v2, v3
	v_lshlrev_b32_e32 v3, 16, v198
	v_lshlrev_b32_e32 v2, 16, v196
	v_pk_mul_f32 v[2:3], v[108:109], v[2:3]
	s_nop 0
	v_add_f32_e32 v2, v10, v2
	v_add_f32_e32 v10, v2, v3
	v_and_b32_e32 v3, 0xffff0000, v198
	v_and_b32_e32 v2, 0xffff0000, v196
	v_pk_mul_f32 v[2:3], v[100:101], v[2:3]
	s_nop 0
	v_add_f32_e32 v2, v11, v2
	v_add_f32_e32 v11, v2, v3
	v_lshlrev_b32_e32 v3, 16, v199
	v_lshlrev_b32_e32 v2, 16, v197
	v_pk_mul_f32 v[2:3], v[96:97], v[2:3]
	v_cvt_pk_bf16_f32 v10, v10, v11
	s_nop 0
	v_add_f32_e32 v2, v128, v2
	v_add_f32_e32 v96, v2, v3
	v_and_b32_e32 v3, 0xffff0000, v199
	v_and_b32_e32 v2, 0xffff0000, v197
	v_pk_mul_f32 v[2:3], v[94:95], v[2:3]
	v_lshlrev_b32_e32 v95, 16, v194
	v_add_f32_e32 v2, v126, v2
	v_add_f32_e32 v2, v2, v3
	v_cvt_pk_bf16_f32 v11, v96, v2
	v_lshlrev_b64 v[2:3], 12, v[162:163]
	v_lshl_add_u64 v[2:3], s[72:73], 0, v[2:3]
	v_lshlrev_b32_e32 v94, 16, v192
	v_lshl_add_u64 v[2:3], v[2:3], 0, v[148:149]
	v_pk_mul_f32 v[94:95], v[124:125], v[94:95]
	global_store_dwordx2 v[2:3], v[10:11], off nt
	v_add_f32_e32 v11, 0, v94
	v_add_f32_e32 v11, v11, v95
	v_and_b32_e32 v95, 0xffff0000, v194
	v_and_b32_e32 v94, 0xffff0000, v192
	v_pk_mul_f32 v[94:95], v[122:123], v[94:95]
	v_or_b32_e32 v10, 16, v162
	v_add_f32_e32 v94, 0, v94
	v_add_f32_e32 v96, v94, v95
	v_lshlrev_b32_e32 v95, 16, v195
	v_lshlrev_b32_e32 v94, 16, v193
	v_pk_mul_f32 v[94:95], v[120:121], v[94:95]
	s_nop 0
	v_add_f32_e32 v94, 0, v94
	v_add_f32_e32 v97, v94, v95
	v_and_b32_e32 v95, 0xffff0000, v195
	v_and_b32_e32 v94, 0xffff0000, v193
	v_pk_mul_f32 v[94:95], v[118:119], v[94:95]
	s_nop 0
	v_add_f32_e32 v94, 0, v94
	v_add_f32_e32 v100, v94, v95
	v_lshlrev_b32_e32 v95, 16, v190
	v_lshlrev_b32_e32 v94, 16, v188
	v_pk_mul_f32 v[92:93], v[92:93], v[94:95]
	s_nop 0
	v_add_f32_e32 v11, v11, v92
	v_add_f32_e32 v94, v11, v93
	v_and_b32_e32 v93, 0xffff0000, v190
	v_and_b32_e32 v92, 0xffff0000, v188
	v_pk_mul_f32 v[90:91], v[90:91], v[92:93]
	s_nop 0
	v_add_f32_e32 v11, v96, v90
	v_add_f32_e32 v92, v11, v91
	v_lshlrev_b32_e32 v91, 16, v191
	v_lshlrev_b32_e32 v90, 16, v189
	v_pk_mul_f32 v[88:89], v[88:89], v[90:91]
	s_nop 0
	v_add_f32_e32 v11, v97, v88
	v_add_f32_e32 v90, v11, v89
	v_and_b32_e32 v89, 0xffff0000, v191
	v_and_b32_e32 v88, 0xffff0000, v189
	v_pk_mul_f32 v[86:87], v[86:87], v[88:89]
	s_nop 0
	v_add_f32_e32 v11, v100, v86
	v_add_f32_e32 v87, v11, v87
	v_ashrrev_i32_e32 v11, 31, v10
	v_lshlrev_b64 v[10:11], 12, v[10:11]
	v_lshl_add_u64 v[10:11], s[72:73], 0, v[10:11]
	v_cvt_pk_bf16_f32 v86, v94, v92
	v_cvt_pk_bf16_f32 v87, v90, v87
	v_lshl_add_u64 v[10:11], v[10:11], 0, v[148:149]
	global_store_dwordx2 v[10:11], v[86:87], off nt
	v_lshlrev_b32_e32 v87, 16, v186
	v_lshlrev_b32_e32 v86, 16, v184
	v_pk_mul_f32 v[86:87], v[116:117], v[86:87]
	v_or_b32_e32 v10, 32, v162
	v_add_f32_e32 v11, 0, v86
	v_add_f32_e32 v11, v11, v87
	v_and_b32_e32 v87, 0xffff0000, v186
	v_and_b32_e32 v86, 0xffff0000, v184
	v_pk_mul_f32 v[86:87], v[114:115], v[86:87]
	s_nop 0
	v_add_f32_e32 v86, 0, v86
	v_add_f32_e32 v88, v86, v87
	v_lshlrev_b32_e32 v87, 16, v187
	v_lshlrev_b32_e32 v86, 16, v185
	v_pk_mul_f32 v[86:87], v[112:113], v[86:87]
	s_nop 0
	v_add_f32_e32 v86, 0, v86
	v_add_f32_e32 v89, v86, v87
	v_and_b32_e32 v87, 0xffff0000, v187
	v_and_b32_e32 v86, 0xffff0000, v185
	v_pk_mul_f32 v[86:87], v[110:111], v[86:87]
	s_nop 0
	v_add_f32_e32 v86, 0, v86
	v_add_f32_e32 v90, v86, v87
	v_lshlrev_b32_e32 v87, 16, v182
	v_lshlrev_b32_e32 v86, 16, v180
	v_pk_mul_f32 v[84:85], v[84:85], v[86:87]
	s_nop 0
	v_add_f32_e32 v11, v11, v84
	v_add_f32_e32 v86, v11, v85
	v_and_b32_e32 v85, 0xffff0000, v182
	v_and_b32_e32 v84, 0xffff0000, v180
	v_pk_mul_f32 v[82:83], v[82:83], v[84:85]
	s_nop 0
	v_add_f32_e32 v11, v88, v82
	v_add_f32_e32 v84, v11, v83
	v_lshlrev_b32_e32 v83, 16, v183
	v_lshlrev_b32_e32 v82, 16, v181
	v_pk_mul_f32 v[80:81], v[80:81], v[82:83]
	s_nop 0
	v_add_f32_e32 v11, v89, v80
	v_add_f32_e32 v82, v11, v81
	v_and_b32_e32 v81, 0xffff0000, v183
	v_and_b32_e32 v80, 0xffff0000, v181
	v_pk_mul_f32 v[78:79], v[78:79], v[80:81]
	s_nop 0
	v_add_f32_e32 v11, v90, v78
	v_add_f32_e32 v79, v11, v79
	v_ashrrev_i32_e32 v11, 31, v10
	v_lshlrev_b64 v[10:11], 12, v[10:11]
	v_lshl_add_u64 v[10:11], s[72:73], 0, v[10:11]
	v_cvt_pk_bf16_f32 v78, v86, v84
	v_cvt_pk_bf16_f32 v79, v82, v79
	v_lshl_add_u64 v[10:11], v[10:11], 0, v[148:149]
	global_store_dwordx2 v[10:11], v[78:79], off nt
	v_lshlrev_b32_e32 v79, 16, v178
	v_lshlrev_b32_e32 v78, 16, v176
	v_pk_mul_f32 v[78:79], v[106:107], v[78:79]
	v_or_b32_e32 v10, 48, v162
	v_add_f32_e32 v11, 0, v78
	v_add_f32_e32 v11, v11, v79
	v_and_b32_e32 v79, 0xffff0000, v178
	v_and_b32_e32 v78, 0xffff0000, v176
	v_pk_mul_f32 v[78:79], v[104:105], v[78:79]
	s_nop 0
	v_add_f32_e32 v78, 0, v78
	v_add_f32_e32 v80, v78, v79
	v_lshlrev_b32_e32 v79, 16, v179
	v_lshlrev_b32_e32 v78, 16, v177
	v_pk_mul_f32 v[78:79], v[102:103], v[78:79]
	s_nop 0
	v_add_f32_e32 v78, 0, v78
	v_add_f32_e32 v81, v78, v79
	v_and_b32_e32 v79, 0xffff0000, v179
	v_and_b32_e32 v78, 0xffff0000, v177
	v_pk_mul_f32 v[78:79], v[98:99], v[78:79]
	s_nop 0
	v_add_f32_e32 v78, 0, v78
	v_add_f32_e32 v82, v78, v79
	v_lshlrev_b32_e32 v79, 16, v174
	v_lshlrev_b32_e32 v78, 16, v172
	v_pk_mul_f32 v[76:77], v[76:77], v[78:79]
	s_nop 0
	v_add_f32_e32 v11, v11, v76
	v_add_f32_e32 v78, v11, v77
	v_and_b32_e32 v77, 0xffff0000, v174
	v_and_b32_e32 v76, 0xffff0000, v172
	v_pk_mul_f32 v[74:75], v[74:75], v[76:77]
	s_nop 0
	v_add_f32_e32 v11, v80, v74
	v_add_f32_e32 v76, v11, v75
	v_lshlrev_b32_e32 v75, 16, v175
	v_lshlrev_b32_e32 v74, 16, v173
	v_pk_mul_f32 v[70:71], v[70:71], v[74:75]
	s_nop 0
	v_add_f32_e32 v11, v81, v70
	v_add_f32_e32 v74, v11, v71
	v_and_b32_e32 v71, 0xffff0000, v175
	v_and_b32_e32 v70, 0xffff0000, v173
	v_pk_mul_f32 v[66:67], v[66:67], v[70:71]
	s_nop 0
	v_add_f32_e32 v11, v82, v66
	v_add_f32_e32 v67, v11, v67
	v_ashrrev_i32_e32 v11, 31, v10
	v_lshlrev_b64 v[10:11], 12, v[10:11]
	v_lshl_add_u64 v[10:11], s[72:73], 0, v[10:11]
	v_lshl_add_u64 v[10:11], v[10:11], 0, v[148:149]
	v_cvt_pk_bf16_f32 v66, v78, v76
	v_cvt_pk_bf16_f32 v67, v74, v67
	global_store_dwordx2 v[10:11], v[66:67], off nt
	v_lshlrev_b32_e32 v11, 16, v170
	v_lshlrev_b32_e32 v10, 16, v168
	v_pk_mul_f32 v[10:11], v[72:73], v[10:11]
	s_nop 0
	v_add_f32_e32 v10, 0, v10
	v_add_f32_e32 v66, v10, v11
	v_and_b32_e32 v11, 0xffff0000, v170
	v_and_b32_e32 v10, 0xffff0000, v168
	v_pk_mul_f32 v[10:11], v[68:69], v[10:11]
	s_nop 0
	v_add_f32_e32 v10, 0, v10
	v_add_f32_e32 v67, v10, v11
	v_lshlrev_b32_e32 v11, 16, v171
	v_lshlrev_b32_e32 v10, 16, v169
	v_pk_mul_f32 v[10:11], v[64:65], v[10:11]
	s_nop 0
	v_add_f32_e32 v10, 0, v10
	v_add_f32_e32 v64, v10, v11
	v_and_b32_e32 v11, 0xffff0000, v171
	v_and_b32_e32 v10, 0xffff0000, v169
	v_pk_mul_f32 v[10:11], v[62:63], v[10:11]
	s_nop 0
	v_add_f32_e32 v10, 0, v10
	v_add_f32_e32 v62, v10, v11
	v_lshlrev_b32_e32 v11, 16, v166
	v_lshlrev_b32_e32 v10, 16, v164
	v_pk_mul_f32 v[10:11], v[44:45], v[10:11]
	s_nop 0
	v_add_f32_e32 v10, v66, v10
	v_add_f32_e32 v44, v10, v11
	v_and_b32_e32 v11, 0xffff0000, v166
	v_and_b32_e32 v10, 0xffff0000, v164
	v_pk_mul_f32 v[10:11], v[36:37], v[10:11]
	s_nop 0
	v_add_f32_e32 v10, v67, v10
	v_add_f32_e32 v36, v10, v11
	v_lshlrev_b32_e32 v11, 16, v167
	v_lshlrev_b32_e32 v10, 16, v165
	v_pk_mul_f32 v[10:11], v[32:33], v[10:11]
	s_nop 0
	v_add_f32_e32 v10, v64, v10
	v_add_f32_e32 v32, v10, v11
	v_and_b32_e32 v11, 0xffff0000, v167
	v_and_b32_e32 v10, 0xffff0000, v165
	v_pk_mul_f32 v[10:11], v[30:31], v[10:11]
	v_add_co_u32_e32 v30, vcc, s64, v2
	v_add_f32_e32 v10, v62, v10
	v_add_f32_e32 v11, v10, v11
	v_cvt_pk_bf16_f32 v10, v44, v36
	v_cvt_pk_bf16_f32 v11, v32, v11
	v_addc_co_u32_e32 v31, vcc, 0, v3, vcc
	global_store_dwordx2 v[30:31], v[10:11], off nt
	v_lshlrev_b32_e32 v11, 16, v160
	v_lshlrev_b32_e32 v10, 16, v158
	v_pk_mul_f32 v[10:11], v[60:61], v[10:11]
	s_nop 0
	v_add_f32_e32 v10, 0, v10
	v_add_f32_e32 v30, v10, v11
	v_and_b32_e32 v11, 0xffff0000, v160
	v_and_b32_e32 v10, 0xffff0000, v158
	v_pk_mul_f32 v[10:11], v[58:59], v[10:11]
	s_nop 0
	v_add_f32_e32 v10, 0, v10
	v_add_f32_e32 v31, v10, v11
	v_lshlrev_b32_e32 v11, 16, v161
	v_lshlrev_b32_e32 v10, 16, v159
	v_pk_mul_f32 v[10:11], v[56:57], v[10:11]
	s_nop 0
	v_add_f32_e32 v10, 0, v10
	v_add_f32_e32 v32, v10, v11
	v_and_b32_e32 v11, 0xffff0000, v161
	v_and_b32_e32 v10, 0xffff0000, v159
	v_pk_mul_f32 v[10:11], v[54:55], v[10:11]
	s_nop 0
	v_add_f32_e32 v10, 0, v10
	v_add_f32_e32 v33, v10, v11
	v_lshlrev_b32_e32 v11, 16, v156
	v_lshlrev_b32_e32 v10, 16, v154
	v_pk_mul_f32 v[10:11], v[28:29], v[10:11]
	s_nop 0
	v_add_f32_e32 v10, v30, v10
	v_add_f32_e32 v28, v10, v11
	v_and_b32_e32 v11, 0xffff0000, v156
	v_and_b32_e32 v10, 0xffff0000, v154
	v_pk_mul_f32 v[10:11], v[26:27], v[10:11]
	s_nop 0
	v_add_f32_e32 v10, v31, v10
	v_add_f32_e32 v26, v10, v11
	v_lshlrev_b32_e32 v11, 16, v157
	v_lshlrev_b32_e32 v10, 16, v155
	v_pk_mul_f32 v[10:11], v[24:25], v[10:11]
	s_nop 0
	v_add_f32_e32 v10, v32, v10
	v_add_f32_e32 v24, v10, v11
	v_and_b32_e32 v11, 0xffff0000, v157
	v_and_b32_e32 v10, 0xffff0000, v155
	v_pk_mul_f32 v[10:11], v[22:23], v[10:11]
	v_add_co_u32_e32 v22, vcc, s31, v2
	v_add_f32_e32 v10, v33, v10
	v_add_f32_e32 v11, v10, v11
	v_cvt_pk_bf16_f32 v10, v28, v26
	v_cvt_pk_bf16_f32 v11, v24, v11
	v_addc_co_u32_e32 v23, vcc, 0, v3, vcc
	global_store_dwordx2 v[22:23], v[10:11], off nt
	v_lshlrev_b32_e32 v11, 16, v152
	v_lshlrev_b32_e32 v10, 16, v150
	v_pk_mul_f32 v[10:11], v[52:53], v[10:11]
	s_nop 0
	v_add_f32_e32 v10, 0, v10
	v_add_f32_e32 v22, v10, v11
	v_and_b32_e32 v11, 0xffff0000, v152
	v_and_b32_e32 v10, 0xffff0000, v150
	v_pk_mul_f32 v[10:11], v[50:51], v[10:11]
	s_nop 0
	v_add_f32_e32 v10, 0, v10
	v_add_f32_e32 v23, v10, v11
	v_lshlrev_b32_e32 v11, 16, v153
	v_lshlrev_b32_e32 v10, 16, v151
	v_pk_mul_f32 v[10:11], v[48:49], v[10:11]
	s_nop 0
	v_add_f32_e32 v10, 0, v10
	v_add_f32_e32 v24, v10, v11
	v_and_b32_e32 v11, 0xffff0000, v153
	v_and_b32_e32 v10, 0xffff0000, v151
	v_pk_mul_f32 v[10:11], v[46:47], v[10:11]
	s_nop 0
	v_add_f32_e32 v10, 0, v10
	v_add_f32_e32 v25, v10, v11
	v_lshlrev_b32_e32 v11, 16, v146
	v_lshlrev_b32_e32 v10, 16, v144
	v_pk_mul_f32 v[10:11], v[20:21], v[10:11]
	s_nop 0
	v_add_f32_e32 v10, v22, v10
	v_add_f32_e32 v20, v10, v11
	v_and_b32_e32 v11, 0xffff0000, v146
	v_and_b32_e32 v10, 0xffff0000, v144
	v_pk_mul_f32 v[10:11], v[18:19], v[10:11]
	s_nop 0
	v_add_f32_e32 v10, v23, v10
	v_add_f32_e32 v18, v10, v11
	v_lshlrev_b32_e32 v11, 16, v147
	v_lshlrev_b32_e32 v10, 16, v145
	v_pk_mul_f32 v[10:11], v[14:15], v[10:11]
	s_nop 0
	v_add_f32_e32 v10, v24, v10
	v_add_f32_e32 v14, v10, v11
	v_and_b32_e32 v11, 0xffff0000, v147
	v_and_b32_e32 v10, 0xffff0000, v145
	v_pk_mul_f32 v[10:11], v[12:13], v[10:11]
	v_add_co_u32_e32 v12, vcc, s65, v2
	v_add_f32_e32 v10, v25, v10
	v_add_f32_e32 v11, v10, v11
	v_cvt_pk_bf16_f32 v10, v20, v18
	v_cvt_pk_bf16_f32 v11, v14, v11
	v_addc_co_u32_e32 v13, vcc, 0, v3, vcc
	global_store_dwordx2 v[12:13], v[10:11], off nt
	v_lshlrev_b32_e32 v11, 16, v142
	v_lshlrev_b32_e32 v10, 16, v140
	v_pk_mul_f32 v[10:11], v[42:43], v[10:11]
	v_add_co_u32_e32 v2, vcc, 0xb0000, v2
	v_add_f32_e32 v10, 0, v10
	v_add_f32_e32 v12, v10, v11
	v_and_b32_e32 v11, 0xffff0000, v142
	v_and_b32_e32 v10, 0xffff0000, v140
	v_pk_mul_f32 v[10:11], v[40:41], v[10:11]
	v_addc_co_u32_e32 v3, vcc, 0, v3, vcc
	v_add_f32_e32 v10, 0, v10
	v_add_f32_e32 v13, v10, v11
	v_lshlrev_b32_e32 v11, 16, v143
	v_lshlrev_b32_e32 v10, 16, v141
	v_pk_mul_f32 v[10:11], v[38:39], v[10:11]
	s_andn2_b64 vcc, exec, s[38:39]
	v_add_f32_e32 v10, 0, v10
	v_add_f32_e32 v14, v10, v11
	v_and_b32_e32 v11, 0xffff0000, v143
	v_and_b32_e32 v10, 0xffff0000, v141
	v_pk_mul_f32 v[10:11], v[34:35], v[10:11]
	s_nop 0
	v_add_f32_e32 v10, 0, v10
	v_add_f32_e32 v15, v10, v11
	v_lshlrev_b32_e32 v11, 16, v138
	v_lshlrev_b32_e32 v10, 16, v136
	v_pk_mul_f32 v[8:9], v[8:9], v[10:11]
	s_nop 0
	v_add_f32_e32 v8, v12, v8
	v_add_f32_e32 v10, v8, v9
	v_and_b32_e32 v9, 0xffff0000, v138
	v_and_b32_e32 v8, 0xffff0000, v136
	v_pk_mul_f32 v[6:7], v[6:7], v[8:9]
	s_nop 0
	v_add_f32_e32 v6, v13, v6
	v_add_f32_e32 v8, v6, v7
	v_lshlrev_b32_e32 v7, 16, v139
	v_lshlrev_b32_e32 v6, 16, v137
	v_pk_mul_f32 v[4:5], v[4:5], v[6:7]
	s_nop 0
	v_add_f32_e32 v4, v14, v4
	v_add_f32_e32 v6, v4, v5
	v_and_b32_e32 v5, 0xffff0000, v139
	v_and_b32_e32 v4, 0xffff0000, v137
	v_pk_mul_f32 v[0:1], v[0:1], v[4:5]
	s_nop 0
	v_add_f32_e32 v0, v15, v0
	v_add_f32_e32 v1, v0, v1
	v_cvt_pk_bf16_f32 v0, v10, v8
	v_cvt_pk_bf16_f32 v1, v6, v1
	global_store_dwordx2 v[2:3], v[0:1], off nt
	s_cbranch_vccnz .LBB0_713
	s_andn2_b64 vcc, exec, s[0:1]
	s_cbranch_vccnz .LBB0_712
	s_barrier
	s_branch .LBB0_712

.LBB0_797:
	v_lshl_add_u64 v[152:153], v[146:147], 2, v[150:151]
	global_load_dwordx4 v[154:157], v[152:153], off offset:16
	global_load_dwordx4 v[158:161], v[152:153], off
	v_lshlrev_b64 v[162:163], 12, v[148:149]
	s_mov_b64 s[4:5], s[6:7]
	s_mov_b64 s[6:7], 0x20000
	s_mov_b64 s[28:29], 0x10000
	s_waitcnt vmcnt(0)
	v_pk_fma_f32 v[150:151], v[128:129], v[144:145], v[160:161]
	v_pk_fma_f32 v[158:159], v[126:127], v[142:143], v[158:159]
	v_pk_fma_f32 v[160:161], v[124:125], v[140:141], v[156:157]
	v_pk_fma_f32 v[156:157], v[122:123], v[138:139], v[154:155]
	v_cvt_pk_bf16_f32 v154, v158, v159
	v_cvt_pk_bf16_f32 v155, v150, v151
	v_lshl_add_u64 v[150:151], s[4:5], 0, v[162:163]
	v_lshl_add_u64 v[150:151], v[146:147], 1, v[150:151]
	v_cvt_pk_bf16_f32 v156, v156, v157
	v_cvt_pk_bf16_f32 v157, v160, v161
	global_store_dwordx4 v[150:151], v[154:157], off nt
	global_load_dwordx4 v[154:157], v[152:153], off offset:528
	s_nop 0
	global_load_dwordx4 v[158:161], v[152:153], off offset:512
	v_lshl_add_u64 v[164:165], v[150:151], 0, s[28:29]
	s_mov_b64 s[28:29], 0x40000
	s_waitcnt vmcnt(1)
	v_pk_fma_f32 v[162:163], v[112:113], v[132:133], v[156:157]
	s_waitcnt vmcnt(0)
	v_pk_fma_f32 v[158:159], v[118:119], v[134:135], v[158:159]
	v_pk_fma_f32 v[156:157], v[110:111], v[130:131], v[154:155]
	v_cvt_pk_bf16_f32 v154, v158, v159
	v_pk_fma_f32 v[160:161], v[120:121], v[136:137], v[160:161]
	s_nop 0
	v_cvt_pk_bf16_f32 v155, v160, v161
	v_cvt_pk_bf16_f32 v156, v156, v157
	v_cvt_pk_bf16_f32 v157, v162, v163
	global_store_dwordx4 v[150:151], v[154:157], off offset:256 nt
	v_lshl_add_u64 v[162:163], v[152:153], 0, s[6:7]
	s_nop 0
	v_add_co_u32_e32 v154, vcc, s17, v152
	s_nop 1
	v_addc_co_u32_e32 v155, vcc, 0, v153, vcc
	global_load_dwordx4 v[154:157], v[154:155], off
	s_nop 0
	global_load_dwordx4 v[158:161], v[162:163], off offset:16
	s_waitcnt vmcnt(1)
	v_pk_fma_f32 v[156:157], v[116:117], v[144:145], v[156:157]
	v_pk_fma_f32 v[154:155], v[114:115], v[142:143], v[154:155]
	s_waitcnt vmcnt(0)
	v_pk_fma_f32 v[158:159], v[106:107], v[138:139], v[158:159]
	v_cvt_pk_bf16_f32 v154, v154, v155
	v_cvt_pk_bf16_f32 v155, v156, v157
	v_pk_fma_f32 v[160:161], v[108:109], v[140:141], v[160:161]
	v_cvt_pk_bf16_f32 v156, v158, v159
	v_add_co_u32_e32 v158, vcc, s67, v150
	v_cvt_pk_bf16_f32 v157, v160, v161
	s_nop 1
	v_addc_co_u32_e32 v159, vcc, 0, v151, vcc
	global_store_dwordx4 v[158:159], v[154:157], off nt
	global_load_dwordx4 v[154:157], v[162:163], off offset:528
	s_nop 0
	global_load_dwordx4 v[158:161], v[162:163], off offset:512
	s_waitcnt vmcnt(1)
	v_pk_fma_f32 v[162:163], v[96:97], v[132:133], v[156:157]
	s_waitcnt vmcnt(0)
	v_pk_fma_f32 v[158:159], v[102:103], v[134:135], v[158:159]
	v_pk_fma_f32 v[156:157], v[94:95], v[130:131], v[154:155]
	v_cvt_pk_bf16_f32 v154, v158, v159
	v_pk_fma_f32 v[160:161], v[104:105], v[136:137], v[160:161]
	s_nop 0
	v_cvt_pk_bf16_f32 v155, v160, v161
	v_cvt_pk_bf16_f32 v156, v156, v157
	v_cvt_pk_bf16_f32 v157, v162, v163
	global_store_dwordx4 v[164:165], v[154:157], off offset:256 nt
	v_lshl_add_u64 v[162:163], v[152:153], 0, s[28:29]
	v_lshl_add_u64 v[164:165], v[150:151], 0, s[6:7]
	v_add_co_u32_e32 v154, vcc, s20, v152
	s_mov_b64 s[6:7], 0x60000
	s_nop 0
	v_addc_co_u32_e32 v155, vcc, 0, v153, vcc
	global_load_dwordx4 v[154:157], v[154:155], off
	s_nop 0
	global_load_dwordx4 v[158:161], v[162:163], off offset:16
	s_mov_b64 s[28:29], 0x30000
	s_waitcnt vmcnt(1)
	v_pk_fma_f32 v[156:157], v[100:101], v[144:145], v[156:157]
	v_pk_fma_f32 v[154:155], v[98:99], v[142:143], v[154:155]
	s_waitcnt vmcnt(0)
	v_pk_fma_f32 v[158:159], v[90:91], v[138:139], v[158:159]
	v_cvt_pk_bf16_f32 v154, v154, v155
	v_cvt_pk_bf16_f32 v155, v156, v157
	v_pk_fma_f32 v[160:161], v[92:93], v[140:141], v[160:161]
	v_cvt_pk_bf16_f32 v156, v158, v159
	v_add_co_u32_e32 v158, vcc, s17, v150
	v_cvt_pk_bf16_f32 v157, v160, v161
	s_nop 1
	v_addc_co_u32_e32 v159, vcc, 0, v151, vcc
	global_store_dwordx4 v[158:159], v[154:157], off nt
	global_load_dwordx4 v[154:157], v[162:163], off offset:528
	s_nop 0
	global_load_dwordx4 v[158:161], v[162:163], off offset:512
	s_waitcnt vmcnt(1)
	v_pk_fma_f32 v[162:163], v[80:81], v[132:133], v[156:157]
	s_waitcnt vmcnt(0)
	v_pk_fma_f32 v[158:159], v[86:87], v[134:135], v[158:159]
	v_pk_fma_f32 v[156:157], v[78:79], v[130:131], v[154:155]
	v_cvt_pk_bf16_f32 v154, v158, v159
	v_pk_fma_f32 v[160:161], v[88:89], v[136:137], v[160:161]
	s_nop 0
	v_cvt_pk_bf16_f32 v155, v160, v161
	v_cvt_pk_bf16_f32 v156, v156, v157
	v_cvt_pk_bf16_f32 v157, v162, v163
	global_store_dwordx4 v[164:165], v[154:157], off offset:256 nt
	v_lshl_add_u64 v[162:163], v[152:153], 0, s[6:7]
	s_mov_b64 s[6:7], 0x100000
	v_add_co_u32_e32 v154, vcc, s21, v152
	v_lshl_add_u64 v[164:165], v[150:151], 0, s[28:29]
	s_nop 0
	v_addc_co_u32_e32 v155, vcc, 0, v153, vcc
	global_load_dwordx4 v[154:157], v[154:155], off
	s_nop 0
	global_load_dwordx4 v[158:161], v[162:163], off offset:16
	s_mov_b64 s[28:29], 0x80000
	s_waitcnt vmcnt(1)
	v_pk_fma_f32 v[156:157], v[84:85], v[144:145], v[156:157]
	v_pk_fma_f32 v[154:155], v[82:83], v[142:143], v[154:155]
	s_waitcnt vmcnt(0)
	v_pk_fma_f32 v[158:159], v[74:75], v[138:139], v[158:159]
	v_cvt_pk_bf16_f32 v154, v154, v155
	v_cvt_pk_bf16_f32 v155, v156, v157
	v_pk_fma_f32 v[160:161], v[76:77], v[140:141], v[160:161]
	v_cvt_pk_bf16_f32 v156, v158, v159
	v_add_co_u32_e32 v158, vcc, s74, v150
	v_cvt_pk_bf16_f32 v157, v160, v161
	s_nop 1
	v_addc_co_u32_e32 v159, vcc, 0, v151, vcc
	global_store_dwordx4 v[158:159], v[154:157], off nt
	global_load_dwordx4 v[154:157], v[162:163], off offset:528
	s_nop 0
	global_load_dwordx4 v[158:161], v[162:163], off offset:512
	s_waitcnt vmcnt(1)
	v_pk_fma_f32 v[162:163], v[68:69], v[132:133], v[156:157]
	v_pk_fma_f32 v[156:157], v[66:67], v[130:131], v[154:155]
	s_waitcnt vmcnt(0)
	v_pk_fma_f32 v[160:161], v[72:73], v[136:137], v[160:161]
	v_pk_fma_f32 v[158:159], v[70:71], v[134:135], v[158:159]
	s_nop 0
	v_cvt_pk_bf16_f32 v154, v158, v159
	v_cvt_pk_bf16_f32 v155, v160, v161
	v_cvt_pk_bf16_f32 v156, v156, v157
	v_cvt_pk_bf16_f32 v157, v162, v163
	v_lshl_add_u64 v[162:163], v[152:153], 0, s[6:7]
	s_mov_b32 s6, 0x100000
	global_store_dwordx4 v[164:165], v[154:157], off offset:256 nt
	v_lshl_add_u64 v[164:165], v[150:151], 0, s[28:29]
	s_mov_b64 s[28:29], 0x90000
	v_add_co_u32_e32 v154, vcc, s6, v152
	s_mov_b64 s[6:7], 0x120000
	s_nop 0
	v_addc_co_u32_e32 v155, vcc, 0, v153, vcc
	global_load_dwordx4 v[154:157], v[154:155], off
	s_nop 0
	global_load_dwordx4 v[158:161], v[162:163], off offset:16
	s_waitcnt vmcnt(1)
	v_pk_fma_f32 v[156:157], v[64:65], v[144:145], v[156:157]
	v_pk_fma_f32 v[154:155], v[62:63], v[142:143], v[154:155]
	s_waitcnt vmcnt(0)
	v_pk_fma_f32 v[158:159], v[58:59], v[138:139], v[158:159]
	v_cvt_pk_bf16_f32 v154, v154, v155
	v_cvt_pk_bf16_f32 v155, v156, v157
	v_pk_fma_f32 v[160:161], v[60:61], v[140:141], v[160:161]
	v_cvt_pk_bf16_f32 v156, v158, v159
	v_add_co_u32_e32 v158, vcc, s64, v150
	v_cvt_pk_bf16_f32 v157, v160, v161
	s_nop 1
	v_addc_co_u32_e32 v159, vcc, 0, v151, vcc
	global_store_dwordx4 v[158:159], v[154:157], off nt
	global_load_dwordx4 v[154:157], v[162:163], off offset:528
	s_nop 0
	global_load_dwordx4 v[158:161], v[162:163], off offset:512
	s_waitcnt vmcnt(1)
	v_pk_fma_f32 v[162:163], v[48:49], v[132:133], v[156:157]
	v_pk_fma_f32 v[156:157], v[46:47], v[130:131], v[154:155]
	s_waitcnt vmcnt(0)
	v_pk_fma_f32 v[160:161], v[56:57], v[136:137], v[160:161]
	v_pk_fma_f32 v[158:159], v[54:55], v[134:135], v[158:159]
	s_nop 0
	v_cvt_pk_bf16_f32 v154, v158, v159
	v_cvt_pk_bf16_f32 v155, v160, v161
	v_cvt_pk_bf16_f32 v156, v156, v157
	v_cvt_pk_bf16_f32 v157, v162, v163
	v_lshl_add_u64 v[162:163], v[152:153], 0, s[6:7]
	s_mov_b32 s6, 0x120000
	global_store_dwordx4 v[164:165], v[154:157], off offset:256 nt
	v_lshl_add_u64 v[164:165], v[150:151], 0, s[28:29]
	s_mov_b64 s[28:29], 0xa0000
	v_add_co_u32_e32 v154, vcc, s6, v152
	s_mov_b64 s[6:7], 0x140000
	s_nop 0
	v_addc_co_u32_e32 v155, vcc, 0, v153, vcc
	global_load_dwordx4 v[154:157], v[154:155], off
	s_nop 0
	global_load_dwordx4 v[158:161], v[162:163], off offset:16
	s_waitcnt vmcnt(1)
	v_pk_fma_f32 v[156:157], v[52:53], v[144:145], v[156:157]
	v_pk_fma_f32 v[154:155], v[50:51], v[142:143], v[154:155]
	s_waitcnt vmcnt(0)
	v_pk_fma_f32 v[158:159], v[42:43], v[138:139], v[158:159]
	v_cvt_pk_bf16_f32 v154, v154, v155
	v_cvt_pk_bf16_f32 v155, v156, v157
	v_pk_fma_f32 v[160:161], v[44:45], v[140:141], v[160:161]
	v_cvt_pk_bf16_f32 v156, v158, v159
	v_add_co_u32_e32 v158, vcc, s31, v150
	v_cvt_pk_bf16_f32 v157, v160, v161
	s_nop 1
	v_addc_co_u32_e32 v159, vcc, 0, v151, vcc
	global_store_dwordx4 v[158:159], v[154:157], off nt
	global_load_dwordx4 v[154:157], v[162:163], off offset:528
	s_nop 0
	global_load_dwordx4 v[158:161], v[162:163], off offset:512
	s_waitcnt vmcnt(1)
	v_pk_fma_f32 v[162:163], v[32:33], v[132:133], v[156:157]
	v_pk_fma_f32 v[156:157], v[30:31], v[130:131], v[154:155]
	s_waitcnt vmcnt(0)
	v_pk_fma_f32 v[160:161], v[40:41], v[136:137], v[160:161]
	v_pk_fma_f32 v[158:159], v[38:39], v[134:135], v[158:159]
	s_nop 0
	v_cvt_pk_bf16_f32 v154, v158, v159
	v_cvt_pk_bf16_f32 v155, v160, v161
	v_cvt_pk_bf16_f32 v156, v156, v157
	v_cvt_pk_bf16_f32 v157, v162, v163
	v_lshl_add_u64 v[162:163], v[152:153], 0, s[6:7]
	s_mov_b32 s6, 0x140000
	global_store_dwordx4 v[164:165], v[154:157], off offset:256 nt
	v_lshl_add_u64 v[164:165], v[150:151], 0, s[28:29]
	s_mov_b64 s[28:29], 0xb0000
	v_add_co_u32_e32 v154, vcc, s6, v152
	s_mov_b64 s[6:7], 0x160000
	s_nop 0
	v_addc_co_u32_e32 v155, vcc, 0, v153, vcc
	global_load_dwordx4 v[154:157], v[154:155], off
	s_nop 0
	global_load_dwordx4 v[158:161], v[162:163], off offset:16
	s_waitcnt vmcnt(1)
	v_pk_fma_f32 v[156:157], v[36:37], v[144:145], v[156:157]
	v_pk_fma_f32 v[154:155], v[34:35], v[142:143], v[154:155]
	s_waitcnt vmcnt(0)
	v_pk_fma_f32 v[158:159], v[26:27], v[138:139], v[158:159]
	v_cvt_pk_bf16_f32 v154, v154, v155
	v_cvt_pk_bf16_f32 v155, v156, v157
	v_pk_fma_f32 v[160:161], v[28:29], v[140:141], v[160:161]
	v_cvt_pk_bf16_f32 v156, v158, v159
	v_add_co_u32_e32 v158, vcc, s65, v150
	v_cvt_pk_bf16_f32 v157, v160, v161
	s_nop 1
	v_addc_co_u32_e32 v159, vcc, 0, v151, vcc
	global_store_dwordx4 v[158:159], v[154:157], off nt
	global_load_dwordx4 v[154:157], v[162:163], off offset:528
	s_nop 0
	global_load_dwordx4 v[158:161], v[162:163], off offset:512
	s_waitcnt vmcnt(1)
	v_pk_fma_f32 v[162:163], v[14:15], v[132:133], v[156:157]
	s_waitcnt vmcnt(0)
	v_pk_fma_f32 v[160:161], v[24:25], v[136:137], v[160:161]
	v_pk_fma_f32 v[158:159], v[22:23], v[134:135], v[158:159]
	v_pk_fma_f32 v[156:157], v[12:13], v[130:131], v[154:155]
	v_cvt_pk_bf16_f32 v154, v158, v159
	v_cvt_pk_bf16_f32 v155, v160, v161
	v_lshl_add_u64 v[160:161], v[152:153], 0, s[6:7]
	s_mov_b32 s6, 0x160000
	v_add_co_u32_e32 v152, vcc, s6, v152
	v_cvt_pk_bf16_f32 v156, v156, v157
	v_cvt_pk_bf16_f32 v157, v162, v163
	global_store_dwordx4 v[164:165], v[154:157], off offset:256 nt
	s_nop 0
	v_addc_co_u32_e32 v153, vcc, 0, v153, vcc
	global_load_dwordx4 v[152:155], v[152:153], off
	s_nop 0
	global_load_dwordx4 v[156:159], v[160:161], off offset:16
	s_mov_b32 s6, 0xb0000
	s_waitcnt vmcnt(1)
	v_pk_fma_f32 v[154:155], v[20:21], v[144:145], v[154:155]
	v_pk_fma_f32 v[152:153], v[18:19], v[142:143], v[152:153]
	s_waitcnt vmcnt(0)
	v_pk_fma_f32 v[158:159], v[10:11], v[140:141], v[158:159]
	v_pk_fma_f32 v[156:157], v[8:9], v[138:139], v[156:157]
	v_cvt_pk_bf16_f32 v152, v152, v153
	v_cvt_pk_bf16_f32 v153, v154, v155
	s_nop 0
	v_cvt_pk_bf16_f32 v154, v156, v157
	v_cvt_pk_bf16_f32 v155, v158, v159
	v_lshl_add_u64 v[158:159], v[150:151], 0, s[28:29]
	v_add_co_u32_e32 v150, vcc, s6, v150
	s_nop 1
	v_addc_co_u32_e32 v151, vcc, 0, v151, vcc
	global_store_dwordx4 v[150:151], v[152:155], off nt
	global_load_dwordx4 v[150:153], v[160:161], off offset:528
	s_nop 0
	global_load_dwordx4 v[154:157], v[160:161], off offset:512
	s_waitcnt vmcnt(1)
	v_pk_fma_f32 v[160:161], v[2:3], v[132:133], v[152:153]
	v_pk_fma_f32 v[152:153], v[0:1], v[130:131], v[150:151]
	s_waitcnt vmcnt(0)
	v_pk_fma_f32 v[156:157], v[6:7], v[136:137], v[156:157]
	v_pk_fma_f32 v[154:155], v[4:5], v[134:135], v[154:155]
	s_nop 0
	v_cvt_pk_bf16_f32 v150, v154, v155
	v_cvt_pk_bf16_f32 v151, v156, v157
	v_cvt_pk_bf16_f32 v152, v152, v153
	v_cvt_pk_bf16_f32 v153, v160, v161
	global_store_dwordx4 v[158:159], v[150:153], off offset:256 nt
	s_mov_b64 s[6:7], s[8:9]
	s_branch .LBB0_799
.LBB0_798:
	v_ashrrev_i32_e32 v149, 31, v148
	v_lshlrev_b64 v[148:149], 12, v[148:149]
	v_lshl_add_u64 v[148:149], s[4:5], 0, v[148:149]
	v_lshl_add_u64 v[250:251], v[146:147], 1, v[148:149]
	v_add_co_u32_e32 v252, vcc, 0x10000, v250
	global_load_dwordx4 v[226:229], v[250:251], off
	global_load_dwordx4 v[230:233], v[250:251], off offset:256
	v_addc_co_u32_e32 v253, vcc, 0, v251, vcc
	v_add_co_u32_e32 v216, vcc, 0x20000, v250
	global_load_dwordx4 v[234:237], v[252:253], off
	global_load_dwordx4 v[238:241], v[252:253], off offset:256
	v_addc_co_u32_e32 v217, vcc, 0, v251, vcc
	v_add_co_u32_e32 v204, vcc, 0x30000, v250
	global_load_dwordx4 v[242:245], v[216:217], off
	global_load_dwordx4 v[246:249], v[216:217], off offset:256
	v_addc_co_u32_e32 v205, vcc, 0, v251, vcc
	v_add_co_u32_e32 v202, vcc, 0x80000, v250
	global_load_dwordx4 v[182:185], v[204:205], off
	global_load_dwordx4 v[178:181], v[204:205], off offset:256
	v_addc_co_u32_e32 v203, vcc, 0, v251, vcc
	v_add_co_u32_e32 v200, vcc, 0x90000, v250
	global_load_dwordx4 v[174:177], v[202:203], off
	global_load_dwordx4 v[170:173], v[202:203], off offset:256
	v_addc_co_u32_e32 v201, vcc, 0, v251, vcc
	v_add_co_u32_e32 v198, vcc, 0xa0000, v250
	global_load_dwordx4 v[166:169], v[200:201], off
	global_load_dwordx4 v[162:165], v[200:201], off offset:256
	v_addc_co_u32_e32 v199, vcc, 0, v251, vcc
	v_add_co_u32_e32 v196, vcc, 0xb0000, v250
	global_load_dwordx4 v[158:161], v[198:199], off
	global_load_dwordx4 v[154:157], v[198:199], off offset:256
	v_addc_co_u32_e32 v197, vcc, 0, v251, vcc
	global_load_dwordx4 v[150:153], v[196:197], off
	global_load_dwordx4 v[146:149], v[196:197], off offset:256
	s_waitcnt vmcnt(0)
	v_lshlrev_b32_e32 v225, 16, v226
	v_fmac_f32_e32 v225, v126, v142
	v_and_b32_e32 v126, 0xffff0000, v226
	v_fmac_f32_e32 v126, v127, v143
	v_lshlrev_b32_e32 v127, 16, v227
	v_fmac_f32_e32 v127, v128, v144
	v_and_b32_e32 v128, 0xffff0000, v227
	v_fmac_f32_e32 v128, v129, v145
	v_cvt_pk_bf16_f32 v126, v225, v126
	v_cvt_pk_bf16_f32 v127, v127, v128
	v_lshlrev_b32_e32 v128, 16, v228
	v_fmac_f32_e32 v128, v122, v138
	v_and_b32_e32 v122, 0xffff0000, v228
	v_fmac_f32_e32 v122, v123, v139
	v_cvt_pk_bf16_f32 v128, v128, v122
	v_lshlrev_b32_e32 v122, 16, v229
	v_fmac_f32_e32 v122, v124, v140
	v_and_b32_e32 v123, 0xffff0000, v229
	v_fmac_f32_e32 v123, v125, v141
	v_cvt_pk_bf16_f32 v129, v122, v123
	v_lshlrev_b32_e32 v122, 16, v230
	v_fmac_f32_e32 v122, v118, v134
	v_and_b32_e32 v118, 0xffff0000, v230
	v_fmac_f32_e32 v118, v119, v135
	v_lshlrev_b32_e32 v119, 16, v231
	v_fmac_f32_e32 v119, v120, v136
	v_and_b32_e32 v120, 0xffff0000, v231
	v_fmac_f32_e32 v120, v121, v137
	global_store_dwordx4 v[250:251], v[126:129], off nt
	v_cvt_pk_bf16_f32 v118, v122, v118
	v_cvt_pk_bf16_f32 v119, v119, v120
	v_lshlrev_b32_e32 v120, 16, v232
	v_fmac_f32_e32 v120, v110, v130
	v_and_b32_e32 v110, 0xffff0000, v232
	v_fmac_f32_e32 v110, v111, v131
	v_cvt_pk_bf16_f32 v120, v120, v110
	v_lshlrev_b32_e32 v110, 16, v233
	v_and_b32_e32 v111, 0xffff0000, v233
	v_fmac_f32_e32 v110, v112, v132
	v_fmac_f32_e32 v111, v113, v133
	v_cvt_pk_bf16_f32 v121, v110, v111
	v_lshlrev_b32_e32 v110, 16, v234
	v_and_b32_e32 v111, 0xffff0000, v234
	v_fmac_f32_e32 v110, v114, v142
	v_fmac_f32_e32 v111, v115, v143
	global_store_dwordx4 v[250:251], v[118:121], off offset:256 nt
	v_cvt_pk_bf16_f32 v110, v110, v111
	v_lshlrev_b32_e32 v111, 16, v235
	v_and_b32_e32 v112, 0xffff0000, v235
	v_fmac_f32_e32 v111, v116, v144
	v_fmac_f32_e32 v112, v117, v145
	v_cvt_pk_bf16_f32 v111, v111, v112
	v_lshlrev_b32_e32 v112, 16, v236
	v_fmac_f32_e32 v112, v106, v138
	v_and_b32_e32 v106, 0xffff0000, v236
	v_fmac_f32_e32 v106, v107, v139
	v_cvt_pk_bf16_f32 v112, v112, v106
	v_lshlrev_b32_e32 v106, 16, v237
	v_fmac_f32_e32 v106, v108, v140
	v_and_b32_e32 v107, 0xffff0000, v237
	v_fmac_f32_e32 v107, v109, v141
	v_cvt_pk_bf16_f32 v113, v106, v107
	v_lshlrev_b32_e32 v106, 16, v238
	v_fmac_f32_e32 v106, v102, v134
	v_and_b32_e32 v102, 0xffff0000, v238
	v_fmac_f32_e32 v102, v103, v135
	v_lshlrev_b32_e32 v103, 16, v239
	v_fmac_f32_e32 v103, v104, v136
	v_and_b32_e32 v104, 0xffff0000, v239
	v_fmac_f32_e32 v104, v105, v137
	global_store_dwordx4 v[252:253], v[110:113], off nt
	v_cvt_pk_bf16_f32 v102, v106, v102
	v_cvt_pk_bf16_f32 v103, v103, v104
	v_lshlrev_b32_e32 v104, 16, v240
	v_fmac_f32_e32 v104, v94, v130
	v_and_b32_e32 v94, 0xffff0000, v240
	v_fmac_f32_e32 v94, v95, v131
	v_cvt_pk_bf16_f32 v104, v104, v94
	v_lshlrev_b32_e32 v94, 16, v241
	v_and_b32_e32 v95, 0xffff0000, v241
	v_fmac_f32_e32 v94, v96, v132
	v_fmac_f32_e32 v95, v97, v133
	v_cvt_pk_bf16_f32 v105, v94, v95
	v_lshlrev_b32_e32 v94, 16, v242
	v_and_b32_e32 v95, 0xffff0000, v242
	v_fmac_f32_e32 v94, v98, v142
	v_fmac_f32_e32 v95, v99, v143
	global_store_dwordx4 v[252:253], v[102:105], off offset:256 nt
	v_cvt_pk_bf16_f32 v94, v94, v95
	v_lshlrev_b32_e32 v95, 16, v243
	v_and_b32_e32 v96, 0xffff0000, v243
	v_fmac_f32_e32 v95, v100, v144
	v_fmac_f32_e32 v96, v101, v145
	v_cvt_pk_bf16_f32 v95, v95, v96
	v_lshlrev_b32_e32 v96, 16, v244
	v_fmac_f32_e32 v96, v90, v138
	v_and_b32_e32 v90, 0xffff0000, v244
	v_fmac_f32_e32 v90, v91, v139
	v_cvt_pk_bf16_f32 v96, v96, v90
	v_lshlrev_b32_e32 v90, 16, v245
	v_fmac_f32_e32 v90, v92, v140
	v_and_b32_e32 v91, 0xffff0000, v245
	v_fmac_f32_e32 v91, v93, v141
	v_cvt_pk_bf16_f32 v97, v90, v91
	v_lshlrev_b32_e32 v90, 16, v246
	v_fmac_f32_e32 v90, v86, v134
	v_and_b32_e32 v86, 0xffff0000, v246
	v_fmac_f32_e32 v86, v87, v135
	v_lshlrev_b32_e32 v87, 16, v247
	v_fmac_f32_e32 v87, v88, v136
	v_and_b32_e32 v88, 0xffff0000, v247
	v_fmac_f32_e32 v88, v89, v137
	global_store_dwordx4 v[216:217], v[94:97], off nt
	v_cvt_pk_bf16_f32 v86, v90, v86
	v_cvt_pk_bf16_f32 v87, v87, v88
	v_lshlrev_b32_e32 v88, 16, v248
	v_fmac_f32_e32 v88, v78, v130
	v_and_b32_e32 v78, 0xffff0000, v248
	v_fmac_f32_e32 v78, v79, v131
	v_cvt_pk_bf16_f32 v88, v88, v78
	v_lshlrev_b32_e32 v78, 16, v249
	v_and_b32_e32 v79, 0xffff0000, v249
	v_fmac_f32_e32 v78, v80, v132
	v_fmac_f32_e32 v79, v81, v133
	v_cvt_pk_bf16_f32 v89, v78, v79
	v_lshlrev_b32_e32 v78, 16, v182
	v_and_b32_e32 v79, 0xffff0000, v182
	v_fmac_f32_e32 v78, v82, v142
	v_fmac_f32_e32 v79, v83, v143
	global_store_dwordx4 v[216:217], v[86:89], off offset:256 nt
	v_cvt_pk_bf16_f32 v78, v78, v79
	v_lshlrev_b32_e32 v79, 16, v183
	v_and_b32_e32 v80, 0xffff0000, v183
	v_fmac_f32_e32 v79, v84, v144
	v_fmac_f32_e32 v80, v85, v145
	v_cvt_pk_bf16_f32 v79, v79, v80
	v_lshlrev_b32_e32 v80, 16, v184
	v_fmac_f32_e32 v80, v74, v138
	v_and_b32_e32 v74, 0xffff0000, v184
	v_fmac_f32_e32 v74, v75, v139
	v_cvt_pk_bf16_f32 v80, v80, v74
	v_lshlrev_b32_e32 v74, 16, v185
	v_fmac_f32_e32 v74, v76, v140
	v_and_b32_e32 v75, 0xffff0000, v185
	v_fmac_f32_e32 v75, v77, v141
	v_cvt_pk_bf16_f32 v81, v74, v75
	v_lshlrev_b32_e32 v74, 16, v178
	v_fmac_f32_e32 v74, v70, v134
	v_and_b32_e32 v70, 0xffff0000, v178
	v_fmac_f32_e32 v70, v71, v135
	v_lshlrev_b32_e32 v71, 16, v179
	v_fmac_f32_e32 v71, v72, v136
	v_and_b32_e32 v72, 0xffff0000, v179
	v_fmac_f32_e32 v72, v73, v137
	global_store_dwordx4 v[204:205], v[78:81], off nt
	v_cvt_pk_bf16_f32 v70, v74, v70
	v_cvt_pk_bf16_f32 v71, v71, v72
	v_lshlrev_b32_e32 v72, 16, v180
	v_fmac_f32_e32 v72, v66, v130
	v_and_b32_e32 v66, 0xffff0000, v180
	v_fmac_f32_e32 v66, v67, v131
	v_cvt_pk_bf16_f32 v72, v72, v66
	v_lshlrev_b32_e32 v66, 16, v181
	v_fmac_f32_e32 v66, v68, v132
	v_and_b32_e32 v67, 0xffff0000, v181
	v_fmac_f32_e32 v67, v69, v133
	v_cvt_pk_bf16_f32 v73, v66, v67
	v_lshlrev_b32_e32 v66, 16, v174
	v_fmac_f32_e32 v66, v62, v142
	v_and_b32_e32 v62, 0xffff0000, v174
	v_fmac_f32_e32 v62, v63, v143
	v_lshlrev_b32_e32 v63, 16, v175
	v_fmac_f32_e32 v63, v64, v144
	v_and_b32_e32 v64, 0xffff0000, v175
	v_fmac_f32_e32 v64, v65, v145
	global_store_dwordx4 v[204:205], v[70:73], off offset:256 nt
	v_cvt_pk_bf16_f32 v62, v66, v62
	v_cvt_pk_bf16_f32 v63, v63, v64
	v_lshlrev_b32_e32 v64, 16, v176
	v_fmac_f32_e32 v64, v58, v138
	v_and_b32_e32 v58, 0xffff0000, v176
	v_fmac_f32_e32 v58, v59, v139
	v_cvt_pk_bf16_f32 v64, v64, v58
	v_lshlrev_b32_e32 v58, 16, v177
	v_fmac_f32_e32 v58, v60, v140
	v_and_b32_e32 v59, 0xffff0000, v177
	v_fmac_f32_e32 v59, v61, v141
	v_cvt_pk_bf16_f32 v65, v58, v59
	v_lshlrev_b32_e32 v58, 16, v170
	v_fmac_f32_e32 v58, v54, v134
	v_and_b32_e32 v54, 0xffff0000, v170
	v_fmac_f32_e32 v54, v55, v135
	v_lshlrev_b32_e32 v55, 16, v171
	v_fmac_f32_e32 v55, v56, v136
	v_and_b32_e32 v56, 0xffff0000, v171
	v_fmac_f32_e32 v56, v57, v137
	global_store_dwordx4 v[202:203], v[62:65], off nt
	v_cvt_pk_bf16_f32 v54, v58, v54
	v_cvt_pk_bf16_f32 v55, v55, v56
	v_lshlrev_b32_e32 v56, 16, v172
	v_fmac_f32_e32 v56, v46, v130
	v_and_b32_e32 v46, 0xffff0000, v172
	v_fmac_f32_e32 v46, v47, v131
	v_cvt_pk_bf16_f32 v56, v56, v46
	v_lshlrev_b32_e32 v46, 16, v173
	v_and_b32_e32 v47, 0xffff0000, v173
	v_fmac_f32_e32 v46, v48, v132
	v_fmac_f32_e32 v47, v49, v133
	v_cvt_pk_bf16_f32 v57, v46, v47
	v_lshlrev_b32_e32 v46, 16, v166
	v_and_b32_e32 v47, 0xffff0000, v166
	v_fmac_f32_e32 v46, v50, v142
	v_fmac_f32_e32 v47, v51, v143
	global_store_dwordx4 v[202:203], v[54:57], off offset:256 nt
	v_cvt_pk_bf16_f32 v46, v46, v47
	v_lshlrev_b32_e32 v47, 16, v167
	v_and_b32_e32 v48, 0xffff0000, v167
	v_fmac_f32_e32 v47, v52, v144
	v_fmac_f32_e32 v48, v53, v145
	v_cvt_pk_bf16_f32 v47, v47, v48
	v_lshlrev_b32_e32 v48, 16, v168
	v_fmac_f32_e32 v48, v42, v138
	v_and_b32_e32 v42, 0xffff0000, v168
	v_fmac_f32_e32 v42, v43, v139
	v_cvt_pk_bf16_f32 v48, v48, v42
	v_lshlrev_b32_e32 v42, 16, v169
	v_fmac_f32_e32 v42, v44, v140
	v_and_b32_e32 v43, 0xffff0000, v169
	v_fmac_f32_e32 v43, v45, v141
	v_cvt_pk_bf16_f32 v49, v42, v43
	v_lshlrev_b32_e32 v42, 16, v162
	v_fmac_f32_e32 v42, v38, v134
	v_and_b32_e32 v38, 0xffff0000, v162
	v_fmac_f32_e32 v38, v39, v135
	v_lshlrev_b32_e32 v39, 16, v163
	v_fmac_f32_e32 v39, v40, v136
	v_and_b32_e32 v40, 0xffff0000, v163
	v_fmac_f32_e32 v40, v41, v137
	global_store_dwordx4 v[200:201], v[46:49], off nt
	v_cvt_pk_bf16_f32 v38, v42, v38
	v_cvt_pk_bf16_f32 v39, v39, v40
	v_lshlrev_b32_e32 v40, 16, v164
	v_fmac_f32_e32 v40, v30, v130
	v_and_b32_e32 v30, 0xffff0000, v164
	v_fmac_f32_e32 v30, v31, v131
	v_cvt_pk_bf16_f32 v40, v40, v30
	v_lshlrev_b32_e32 v30, 16, v165
	v_and_b32_e32 v31, 0xffff0000, v165
	v_fmac_f32_e32 v30, v32, v132
	v_fmac_f32_e32 v31, v33, v133
	v_cvt_pk_bf16_f32 v41, v30, v31
	v_lshlrev_b32_e32 v30, 16, v158
	v_and_b32_e32 v31, 0xffff0000, v158
	v_fmac_f32_e32 v30, v34, v142
	v_fmac_f32_e32 v31, v35, v143
	global_store_dwordx4 v[200:201], v[38:41], off offset:256 nt
	v_cvt_pk_bf16_f32 v30, v30, v31
	v_lshlrev_b32_e32 v31, 16, v159
	v_and_b32_e32 v32, 0xffff0000, v159
	v_fmac_f32_e32 v31, v36, v144
	v_fmac_f32_e32 v32, v37, v145
	v_cvt_pk_bf16_f32 v31, v31, v32
	v_lshlrev_b32_e32 v32, 16, v160
	v_fmac_f32_e32 v32, v26, v138
	v_and_b32_e32 v26, 0xffff0000, v160
	v_fmac_f32_e32 v26, v27, v139
	v_cvt_pk_bf16_f32 v32, v32, v26
	v_lshlrev_b32_e32 v26, 16, v161
	v_fmac_f32_e32 v26, v28, v140
	v_and_b32_e32 v27, 0xffff0000, v161
	v_fmac_f32_e32 v27, v29, v141
	v_cvt_pk_bf16_f32 v33, v26, v27
	v_lshlrev_b32_e32 v26, 16, v154
	v_fmac_f32_e32 v26, v22, v134
	v_and_b32_e32 v22, 0xffff0000, v154
	v_fmac_f32_e32 v22, v23, v135
	v_lshlrev_b32_e32 v23, 16, v155
	v_fmac_f32_e32 v23, v24, v136
	v_and_b32_e32 v24, 0xffff0000, v155
	v_fmac_f32_e32 v24, v25, v137
	global_store_dwordx4 v[198:199], v[30:33], off nt
	v_cvt_pk_bf16_f32 v22, v26, v22
	v_cvt_pk_bf16_f32 v23, v23, v24
	v_lshlrev_b32_e32 v24, 16, v156
	v_fmac_f32_e32 v24, v12, v130
	v_and_b32_e32 v12, 0xffff0000, v156
	v_fmac_f32_e32 v12, v13, v131
	v_cvt_pk_bf16_f32 v24, v24, v12
	v_lshlrev_b32_e32 v12, 16, v157
	v_and_b32_e32 v13, 0xffff0000, v157
	v_fmac_f32_e32 v12, v14, v132
	v_fmac_f32_e32 v13, v15, v133
	v_cvt_pk_bf16_f32 v25, v12, v13
	v_lshlrev_b32_e32 v12, 16, v150
	v_and_b32_e32 v13, 0xffff0000, v150
	v_fmac_f32_e32 v12, v18, v142
	v_fmac_f32_e32 v13, v19, v143
	global_store_dwordx4 v[198:199], v[22:25], off offset:256 nt
	v_cvt_pk_bf16_f32 v12, v12, v13
	v_lshlrev_b32_e32 v13, 16, v151
	v_and_b32_e32 v14, 0xffff0000, v151
	v_fmac_f32_e32 v13, v20, v144
	v_fmac_f32_e32 v14, v21, v145
	v_cvt_pk_bf16_f32 v13, v13, v14
	v_lshlrev_b32_e32 v14, 16, v152
	v_fmac_f32_e32 v14, v8, v138
	v_and_b32_e32 v8, 0xffff0000, v152
	v_fmac_f32_e32 v8, v9, v139
	v_cvt_pk_bf16_f32 v14, v14, v8
	v_lshlrev_b32_e32 v8, 16, v153
	v_fmac_f32_e32 v8, v10, v140
	v_and_b32_e32 v9, 0xffff0000, v153
	v_fmac_f32_e32 v9, v11, v141
	v_cvt_pk_bf16_f32 v15, v8, v9
	v_lshlrev_b32_e32 v8, 16, v146
	v_fmac_f32_e32 v8, v4, v134
	v_and_b32_e32 v4, 0xffff0000, v146
	v_fmac_f32_e32 v4, v5, v135
	v_lshlrev_b32_e32 v5, 16, v147
	v_fmac_f32_e32 v5, v6, v136
	v_and_b32_e32 v6, 0xffff0000, v147
	v_fmac_f32_e32 v6, v7, v137
	global_store_dwordx4 v[196:197], v[12:15], off nt
	v_cvt_pk_bf16_f32 v4, v8, v4
	v_cvt_pk_bf16_f32 v5, v5, v6
	v_lshlrev_b32_e32 v6, 16, v148
	v_fmac_f32_e32 v6, v0, v130
	v_and_b32_e32 v0, 0xffff0000, v148
	v_fmac_f32_e32 v0, v1, v131
	v_cvt_pk_bf16_f32 v6, v6, v0
	v_lshlrev_b32_e32 v0, 16, v149
	v_and_b32_e32 v1, 0xffff0000, v149
	v_fmac_f32_e32 v0, v2, v132
	v_fmac_f32_e32 v1, v3, v133
	v_cvt_pk_bf16_f32 v7, v0, v1
	global_store_dwordx4 v[196:197], v[4:7], off offset:256 nt

.LBB0_923:
	v_mul_f32_e32 v145, 0xbfb8aa3b, v126
	v_exp_f32_e32 v145, v145
	v_lshl_or_b32 v146, s85, 7, v142
	v_lshl_add_u32 v144, s44, 8, v140
	v_ashrrev_i32_e32 v147, 31, v146
	v_add_f32_e32 v145, 1.0, v145
	v_rcp_f32_e32 v145, v145
	s_andn2_b64 vcc, exec, s[38:39]
	s_mov_b64 s[92:93], 0x2000
	s_mov_b64 s[90:91], s[62:63]
	v_mul_f32_e32 v126, v126, v145
	v_mul_f32_e32 v122, v126, v122
	v_mul_f32_e32 v126, 0xbfb8aa3b, v127
	v_exp_f32_e32 v126, v126
	s_nop 0
	v_add_f32_e32 v126, 1.0, v126
	v_rcp_f32_e32 v126, v126
	s_nop 0
	v_mul_f32_e32 v126, v127, v126
	v_mul_f32_e32 v123, v126, v123
	v_mul_f32_e32 v126, 0xbfb8aa3b, v128
	v_exp_f32_e32 v126, v126
	s_nop 0
	v_add_f32_e32 v126, 1.0, v126
	v_rcp_f32_e32 v126, v126
	s_nop 0
	v_mul_f32_e32 v126, v128, v126
	v_mul_f32_e32 v124, v126, v124
	v_mul_f32_e32 v126, 0xbfb8aa3b, v129
	v_exp_f32_e32 v126, v126
	s_nop 0
	v_add_f32_e32 v126, 1.0, v126
	v_rcp_f32_e32 v126, v126
	s_nop 0
	v_mul_f32_e32 v126, v129, v126
	v_mul_f32_e32 v125, v126, v125
	v_mul_f32_e32 v126, 0xbfb8aa3b, v118
	v_exp_f32_e32 v126, v126
	s_nop 0
	v_add_f32_e32 v126, 1.0, v126
	v_rcp_f32_e32 v126, v126
	s_nop 0
	v_mul_f32_e32 v118, v118, v126
	v_mul_f32_e32 v114, v118, v114
	v_mul_f32_e32 v118, 0xbfb8aa3b, v119
	v_exp_f32_e32 v118, v118
	s_nop 0
	v_add_f32_e32 v118, 1.0, v118
	v_rcp_f32_e32 v118, v118
	s_nop 0
	v_mul_f32_e32 v118, v119, v118
	v_mul_f32_e32 v115, v118, v115
	v_mul_f32_e32 v118, 0xbfb8aa3b, v120
	v_exp_f32_e32 v118, v118
	s_nop 0
	v_add_f32_e32 v118, 1.0, v118
	v_rcp_f32_e32 v118, v118
	s_nop 0
	v_mul_f32_e32 v118, v120, v118
	v_mul_f32_e32 v116, v118, v116
	v_mul_f32_e32 v118, 0xbfb8aa3b, v121
	v_exp_f32_e32 v118, v118
	s_nop 0
	v_add_f32_e32 v118, 1.0, v118
	v_rcp_f32_e32 v118, v118
	s_nop 0
	v_mul_f32_e32 v118, v121, v118
	v_mul_f32_e32 v117, v118, v117
	v_cvt_pk_bf16_f32 v118, v122, v123
	v_cvt_pk_bf16_f32 v119, v124, v125
	v_cvt_pk_bf16_f32 v120, v114, v115
	v_mov_b64_e32 v[114:115], s[70:71]
	v_cvt_pk_bf16_f32 v121, v116, v117
	v_mad_i64_i32 v[122:123], s[28:29], v144, s76, v[114:115]
	v_lshlrev_b64 v[116:117], 1, v[146:147]
	v_lshl_add_u64 v[122:123], v[122:123], 0, v[116:117]
	global_store_dwordx4 v[122:123], v[118:121], off nt
	s_nop 1
	v_mul_f32_e32 v118, 0xbfb8aa3b, v110
	v_exp_f32_e32 v118, v118
	s_nop 0
	v_add_f32_e32 v118, 1.0, v118
	v_rcp_f32_e32 v118, v118
	s_nop 0
	v_mul_f32_e32 v110, v110, v118
	v_mul_f32_e32 v106, v110, v106
	v_mul_f32_e32 v110, 0xbfb8aa3b, v111
	v_exp_f32_e32 v110, v110
	s_nop 0
	v_add_f32_e32 v110, 1.0, v110
	v_rcp_f32_e32 v110, v110
	s_nop 0
	v_mul_f32_e32 v110, v111, v110
	v_mul_f32_e32 v107, v110, v107
	v_mul_f32_e32 v110, 0xbfb8aa3b, v112
	v_exp_f32_e32 v110, v110
	s_nop 0
	v_add_f32_e32 v110, 1.0, v110
	v_rcp_f32_e32 v110, v110
	s_nop 0
	v_mul_f32_e32 v110, v112, v110
	v_mul_f32_e32 v108, v110, v108
	v_mul_f32_e32 v110, 0xbfb8aa3b, v113
	v_exp_f32_e32 v110, v110
	s_nop 0
	v_add_f32_e32 v110, 1.0, v110
	v_rcp_f32_e32 v110, v110
	s_nop 0
	v_mul_f32_e32 v110, v113, v110
	v_mul_f32_e32 v109, v110, v109
	v_mul_f32_e32 v110, 0xbfb8aa3b, v102
	v_exp_f32_e32 v110, v110
	s_nop 0
	v_add_f32_e32 v110, 1.0, v110
	v_rcp_f32_e32 v110, v110
	s_nop 0
	v_mul_f32_e32 v102, v102, v110
	v_mul_f32_e32 v102, v102, v98
	v_mul_f32_e32 v98, 0xbfb8aa3b, v103
	v_exp_f32_e32 v98, v98
	s_nop 0
	v_add_f32_e32 v98, 1.0, v98
	v_rcp_f32_e32 v98, v98
	s_nop 0
	v_mul_f32_e32 v98, v103, v98
	v_mul_f32_e32 v103, v98, v99
	v_mul_f32_e32 v98, 0xbfb8aa3b, v104
	v_exp_f32_e32 v98, v98
	s_nop 0
	v_add_f32_e32 v98, 1.0, v98
	v_rcp_f32_e32 v98, v98
	s_nop 0
	v_mul_f32_e32 v98, v104, v98
	v_mul_f32_e32 v104, v98, v100
	v_mul_f32_e32 v98, 0xbfb8aa3b, v105
	v_exp_f32_e32 v98, v98
	s_nop 0
	v_add_f32_e32 v98, 1.0, v98
	v_rcp_f32_e32 v98, v98
	s_nop 0
	v_mul_f32_e32 v98, v105, v98
	v_mul_f32_e32 v101, v98, v101
	v_cvt_pk_bf16_f32 v98, v106, v107
	v_cvt_pk_bf16_f32 v99, v108, v109
	v_cvt_pk_bf16_f32 v100, v102, v103
	v_or_b32_e32 v102, 16, v144
	v_mad_i64_i32 v[102:103], s[28:29], v102, s76, v[114:115]
	v_lshl_add_u64 v[102:103], v[102:103], 0, v[116:117]
	v_cvt_pk_bf16_f32 v101, v104, v101
	global_store_dwordx4 v[102:103], v[98:101], off nt
	s_nop 1
	v_mul_f32_e32 v98, 0xbfb8aa3b, v94
	v_exp_f32_e32 v98, v98
	s_nop 0
	v_add_f32_e32 v98, 1.0, v98
	v_rcp_f32_e32 v98, v98
	s_nop 0
	v_mul_f32_e32 v94, v94, v98
	v_mul_f32_e32 v90, v94, v90
	v_mul_f32_e32 v94, 0xbfb8aa3b, v95
	v_exp_f32_e32 v94, v94
	s_nop 0
	v_add_f32_e32 v94, 1.0, v94
	v_rcp_f32_e32 v94, v94
	s_nop 0
	v_mul_f32_e32 v94, v95, v94
	v_mul_f32_e32 v91, v94, v91
	v_mul_f32_e32 v94, 0xbfb8aa3b, v96
	v_exp_f32_e32 v94, v94
	s_nop 0
	v_add_f32_e32 v94, 1.0, v94
	v_rcp_f32_e32 v94, v94
	s_nop 0
	v_mul_f32_e32 v94, v96, v94
	v_mul_f32_e32 v92, v94, v92
	v_mul_f32_e32 v94, 0xbfb8aa3b, v97
	v_exp_f32_e32 v94, v94
	s_nop 0
	v_add_f32_e32 v94, 1.0, v94
	v_rcp_f32_e32 v94, v94
	s_nop 0
	v_mul_f32_e32 v94, v97, v94
	v_mul_f32_e32 v93, v94, v93
	v_mul_f32_e32 v94, 0xbfb8aa3b, v86
	v_exp_f32_e32 v94, v94
	s_nop 0
	v_add_f32_e32 v94, 1.0, v94
	v_rcp_f32_e32 v94, v94
	s_nop 0
	v_mul_f32_e32 v86, v86, v94
	v_mul_f32_e32 v86, v86, v82
	v_mul_f32_e32 v82, 0xbfb8aa3b, v87
	v_exp_f32_e32 v82, v82
	s_nop 0
	v_add_f32_e32 v82, 1.0, v82
	v_rcp_f32_e32 v82, v82
	s_nop 0
	v_mul_f32_e32 v82, v87, v82
	v_mul_f32_e32 v87, v82, v83
	v_mul_f32_e32 v82, 0xbfb8aa3b, v88
	v_exp_f32_e32 v82, v82
	s_nop 0
	v_add_f32_e32 v82, 1.0, v82
	v_rcp_f32_e32 v82, v82
	s_nop 0
	v_mul_f32_e32 v82, v88, v82
	v_mul_f32_e32 v88, v82, v84
	v_mul_f32_e32 v82, 0xbfb8aa3b, v89
	v_exp_f32_e32 v82, v82
	s_nop 0
	v_add_f32_e32 v82, 1.0, v82
	v_rcp_f32_e32 v82, v82
	s_nop 0
	v_mul_f32_e32 v82, v89, v82
	v_mul_f32_e32 v85, v82, v85
	v_cvt_pk_bf16_f32 v82, v90, v91
	v_cvt_pk_bf16_f32 v83, v92, v93
	v_cvt_pk_bf16_f32 v84, v86, v87
	v_or_b32_e32 v86, 32, v144
	v_mad_i64_i32 v[86:87], s[28:29], v86, s76, v[114:115]
	v_lshl_add_u64 v[86:87], v[86:87], 0, v[116:117]
	v_cvt_pk_bf16_f32 v85, v88, v85
	global_store_dwordx4 v[86:87], v[82:85], off nt
	s_nop 1
	v_mul_f32_e32 v82, 0xbfb8aa3b, v78
	v_exp_f32_e32 v82, v82
	s_nop 0
	v_add_f32_e32 v82, 1.0, v82
	v_rcp_f32_e32 v82, v82
	s_nop 0
	v_mul_f32_e32 v78, v78, v82
	v_mul_f32_e32 v74, v78, v74
	v_mul_f32_e32 v78, 0xbfb8aa3b, v79
	v_exp_f32_e32 v78, v78
	s_nop 0
	v_add_f32_e32 v78, 1.0, v78
	v_rcp_f32_e32 v78, v78
	s_nop 0
	v_mul_f32_e32 v78, v79, v78
	v_mul_f32_e32 v75, v78, v75
	v_mul_f32_e32 v78, 0xbfb8aa3b, v80
	v_exp_f32_e32 v78, v78
	s_nop 0
	v_add_f32_e32 v78, 1.0, v78
	v_rcp_f32_e32 v78, v78
	s_nop 0
	v_mul_f32_e32 v78, v80, v78
	v_mul_f32_e32 v76, v78, v76
	v_mul_f32_e32 v78, 0xbfb8aa3b, v81
	v_exp_f32_e32 v78, v78
	s_nop 0
	v_add_f32_e32 v78, 1.0, v78
	v_rcp_f32_e32 v78, v78
	s_nop 0
	v_mul_f32_e32 v78, v81, v78
	v_mul_f32_e32 v77, v78, v77
	v_mul_f32_e32 v78, 0xbfb8aa3b, v70
	v_exp_f32_e32 v78, v78
	s_nop 0
	v_add_f32_e32 v78, 1.0, v78
	v_rcp_f32_e32 v78, v78
	s_nop 0
	v_mul_f32_e32 v70, v70, v78
	v_mul_f32_e32 v70, v70, v66
	v_mul_f32_e32 v66, 0xbfb8aa3b, v71
	v_exp_f32_e32 v66, v66
	s_nop 0
	v_add_f32_e32 v66, 1.0, v66
	v_rcp_f32_e32 v66, v66
	s_nop 0
	v_mul_f32_e32 v66, v71, v66
	v_mul_f32_e32 v71, v66, v67
	v_mul_f32_e32 v66, 0xbfb8aa3b, v72
	v_exp_f32_e32 v66, v66
	s_nop 0
	v_add_f32_e32 v66, 1.0, v66
	v_rcp_f32_e32 v66, v66
	s_nop 0
	v_mul_f32_e32 v66, v72, v66
	v_mul_f32_e32 v72, v66, v68
	v_mul_f32_e32 v66, 0xbfb8aa3b, v73
	v_exp_f32_e32 v66, v66
	s_nop 0
	v_add_f32_e32 v66, 1.0, v66
	v_rcp_f32_e32 v66, v66
	s_nop 0
	v_mul_f32_e32 v66, v73, v66
	v_mul_f32_e32 v69, v66, v69
	v_cvt_pk_bf16_f32 v66, v74, v75
	v_cvt_pk_bf16_f32 v67, v76, v77
	v_cvt_pk_bf16_f32 v68, v70, v71
	v_or_b32_e32 v70, 48, v144
	v_mad_i64_i32 v[70:71], s[28:29], v70, s76, v[114:115]
	v_lshl_add_u64 v[70:71], v[70:71], 0, v[116:117]
	v_cvt_pk_bf16_f32 v69, v72, v69
	global_store_dwordx4 v[70:71], v[66:69], off nt
	s_nop 1
	v_mul_f32_e32 v67, 0xbfb8aa3b, v62
	v_exp_f32_e32 v67, v67
	v_add_u32_e32 v66, 0x80, v144
	v_add_f32_e32 v67, 1.0, v67
	v_rcp_f32_e32 v67, v67
	s_nop 0
	v_mul_f32_e32 v62, v62, v67
	v_mul_f32_e32 v58, v62, v58
	v_mul_f32_e32 v62, 0xbfb8aa3b, v63
	v_exp_f32_e32 v62, v62
	s_nop 0
	v_add_f32_e32 v62, 1.0, v62
	v_rcp_f32_e32 v62, v62
	s_nop 0
	v_mul_f32_e32 v62, v63, v62
	v_mul_f32_e32 v59, v62, v59
	v_mul_f32_e32 v62, 0xbfb8aa3b, v64
	v_exp_f32_e32 v62, v62
	s_nop 0
	v_add_f32_e32 v62, 1.0, v62
	v_rcp_f32_e32 v62, v62
	s_nop 0
	v_mul_f32_e32 v62, v64, v62
	v_mul_f32_e32 v60, v62, v60
	v_mul_f32_e32 v62, 0xbfb8aa3b, v65
	v_exp_f32_e32 v62, v62
	s_nop 0
	v_add_f32_e32 v62, 1.0, v62
	v_rcp_f32_e32 v62, v62
	s_nop 0
	v_mul_f32_e32 v62, v65, v62
	v_mul_f32_e32 v61, v62, v61
	v_mul_f32_e32 v62, 0xbfb8aa3b, v54
	v_exp_f32_e32 v62, v62
	s_nop 0
	v_add_f32_e32 v62, 1.0, v62
	v_rcp_f32_e32 v62, v62
	s_nop 0
	v_mul_f32_e32 v54, v54, v62
	v_mul_f32_e32 v54, v54, v50
	v_mul_f32_e32 v50, 0xbfb8aa3b, v55
	v_exp_f32_e32 v50, v50
	s_nop 0
	v_add_f32_e32 v50, 1.0, v50
	v_rcp_f32_e32 v50, v50
	s_nop 0
	v_mul_f32_e32 v50, v55, v50
	v_mul_f32_e32 v55, v50, v51
	v_mul_f32_e32 v50, 0xbfb8aa3b, v56
	v_exp_f32_e32 v50, v50
	s_nop 0
	v_add_f32_e32 v50, 1.0, v50
	v_rcp_f32_e32 v50, v50
	s_nop 0
	v_mul_f32_e32 v50, v56, v50
	v_mul_f32_e32 v56, v50, v52
	v_mul_f32_e32 v50, 0xbfb8aa3b, v57
	v_exp_f32_e32 v50, v50
	s_nop 0
	v_add_f32_e32 v50, 1.0, v50
	v_rcp_f32_e32 v50, v50
	s_nop 0
	v_mul_f32_e32 v50, v57, v50
	v_mul_f32_e32 v53, v50, v53
	v_cvt_pk_bf16_f32 v50, v58, v59
	v_cvt_pk_bf16_f32 v51, v60, v61
	v_cvt_pk_bf16_f32 v52, v54, v55
	v_mad_i64_i32 v[54:55], s[28:29], v66, s76, v[114:115]
	v_lshl_add_u64 v[54:55], v[54:55], 0, v[116:117]
	v_cvt_pk_bf16_f32 v53, v56, v53
	global_store_dwordx4 v[54:55], v[50:53], off nt
	s_nop 1
	v_mul_f32_e32 v50, 0xbfb8aa3b, v46
	v_exp_f32_e32 v50, v50
	s_nop 0
	v_add_f32_e32 v50, 1.0, v50
	v_rcp_f32_e32 v50, v50
	s_nop 0
	v_mul_f32_e32 v46, v46, v50
	v_mul_f32_e32 v42, v46, v42
	v_mul_f32_e32 v46, 0xbfb8aa3b, v47
	v_exp_f32_e32 v46, v46
	s_nop 0
	v_add_f32_e32 v46, 1.0, v46
	v_rcp_f32_e32 v46, v46
	s_nop 0
	v_mul_f32_e32 v46, v47, v46
	v_mul_f32_e32 v43, v46, v43
	v_mul_f32_e32 v46, 0xbfb8aa3b, v48
	v_exp_f32_e32 v46, v46
	s_nop 0
	v_add_f32_e32 v46, 1.0, v46
	v_rcp_f32_e32 v46, v46
	s_nop 0
	v_mul_f32_e32 v46, v48, v46
	v_mul_f32_e32 v44, v46, v44
	v_mul_f32_e32 v46, 0xbfb8aa3b, v49
	v_exp_f32_e32 v46, v46
	s_nop 0
	v_add_f32_e32 v46, 1.0, v46
	v_rcp_f32_e32 v46, v46
	s_nop 0
	v_mul_f32_e32 v46, v49, v46
	v_mul_f32_e32 v45, v46, v45
	v_mul_f32_e32 v46, 0xbfb8aa3b, v38
	v_exp_f32_e32 v46, v46
	s_nop 0
	v_add_f32_e32 v46, 1.0, v46
	v_rcp_f32_e32 v46, v46
	s_nop 0
	v_mul_f32_e32 v38, v38, v46
	v_mul_f32_e32 v38, v38, v34
	v_mul_f32_e32 v34, 0xbfb8aa3b, v39
	v_exp_f32_e32 v34, v34
	s_nop 0
	v_add_f32_e32 v34, 1.0, v34
	v_rcp_f32_e32 v34, v34
	s_nop 0
	v_mul_f32_e32 v34, v39, v34
	v_mul_f32_e32 v39, v34, v35
	v_mul_f32_e32 v34, 0xbfb8aa3b, v40
	v_exp_f32_e32 v34, v34
	s_nop 0
	v_add_f32_e32 v34, 1.0, v34
	v_rcp_f32_e32 v34, v34
	s_nop 0
	v_mul_f32_e32 v34, v40, v34
	v_mul_f32_e32 v40, v34, v36
	v_mul_f32_e32 v34, 0xbfb8aa3b, v41
	v_exp_f32_e32 v34, v34
	s_nop 0
	v_add_f32_e32 v34, 1.0, v34
	v_rcp_f32_e32 v34, v34
	s_nop 0
	v_mul_f32_e32 v34, v41, v34
	v_mul_f32_e32 v37, v34, v37
	v_cvt_pk_bf16_f32 v34, v42, v43
	v_cvt_pk_bf16_f32 v35, v44, v45
	v_cvt_pk_bf16_f32 v36, v38, v39
	v_add_u32_e32 v38, 0x90, v144
	v_mad_i64_i32 v[38:39], s[28:29], v38, s76, v[114:115]
	v_lshl_add_u64 v[38:39], v[38:39], 0, v[116:117]
	v_cvt_pk_bf16_f32 v37, v40, v37
	global_store_dwordx4 v[38:39], v[34:37], off nt
	s_nop 1
	v_mul_f32_e32 v34, 0xbfb8aa3b, v30
	v_exp_f32_e32 v34, v34
	s_nop 0
	v_add_f32_e32 v34, 1.0, v34
	v_rcp_f32_e32 v34, v34
	s_nop 0
	v_mul_f32_e32 v30, v30, v34
	v_mul_f32_e32 v26, v30, v26
	v_mul_f32_e32 v30, 0xbfb8aa3b, v31
	v_exp_f32_e32 v30, v30
	s_nop 0
	v_add_f32_e32 v30, 1.0, v30
	v_rcp_f32_e32 v30, v30
	s_nop 0
	v_mul_f32_e32 v30, v31, v30
	v_mul_f32_e32 v27, v30, v27
	v_mul_f32_e32 v30, 0xbfb8aa3b, v32
	v_exp_f32_e32 v30, v30
	s_nop 0
	v_add_f32_e32 v30, 1.0, v30
	v_rcp_f32_e32 v30, v30
	s_nop 0
	v_mul_f32_e32 v30, v32, v30
	v_mul_f32_e32 v28, v30, v28
	v_mul_f32_e32 v30, 0xbfb8aa3b, v33
	v_exp_f32_e32 v30, v30
	s_nop 0
	v_add_f32_e32 v30, 1.0, v30
	v_rcp_f32_e32 v30, v30
	s_nop 0
	v_mul_f32_e32 v30, v33, v30
	v_mul_f32_e32 v29, v30, v29
	v_mul_f32_e32 v30, 0xbfb8aa3b, v22
	v_exp_f32_e32 v30, v30
	s_nop 0
	v_add_f32_e32 v30, 1.0, v30
	v_rcp_f32_e32 v30, v30
	s_nop 0
	v_mul_f32_e32 v22, v22, v30
	v_mul_f32_e32 v22, v22, v18
	v_mul_f32_e32 v18, 0xbfb8aa3b, v23
	v_exp_f32_e32 v18, v18
	s_nop 0
	v_add_f32_e32 v18, 1.0, v18
	v_rcp_f32_e32 v18, v18
	s_nop 0
	v_mul_f32_e32 v18, v23, v18
	v_mul_f32_e32 v23, v18, v19
	v_mul_f32_e32 v18, 0xbfb8aa3b, v24
	v_exp_f32_e32 v18, v18
	s_nop 0
	v_add_f32_e32 v18, 1.0, v18
	v_rcp_f32_e32 v18, v18
	s_nop 0
	v_mul_f32_e32 v18, v24, v18
	v_mul_f32_e32 v24, v18, v20
	v_mul_f32_e32 v18, 0xbfb8aa3b, v25
	v_exp_f32_e32 v18, v18
	s_nop 0
	v_add_f32_e32 v18, 1.0, v18
	v_rcp_f32_e32 v18, v18
	s_nop 0
	v_mul_f32_e32 v18, v25, v18
	v_mul_f32_e32 v21, v18, v21
	v_cvt_pk_bf16_f32 v18, v26, v27
	v_cvt_pk_bf16_f32 v19, v28, v29
	v_cvt_pk_bf16_f32 v20, v22, v23
	v_add_u32_e32 v22, 0xa0, v144
	v_mad_i64_i32 v[22:23], s[28:29], v22, s76, v[114:115]
	v_lshl_add_u64 v[22:23], v[22:23], 0, v[116:117]
	v_cvt_pk_bf16_f32 v21, v24, v21
	global_store_dwordx4 v[22:23], v[18:21], off nt
	s_nop 1
	v_mul_f32_e32 v18, 0xbfb8aa3b, v12
	v_exp_f32_e32 v18, v18
	s_nop 0
	v_add_f32_e32 v18, 1.0, v18
	v_rcp_f32_e32 v18, v18
	s_nop 0
	v_mul_f32_e32 v12, v12, v18
	v_mul_f32_e32 v8, v12, v8
	v_mul_f32_e32 v12, 0xbfb8aa3b, v13
	v_exp_f32_e32 v12, v12
	s_nop 0
	v_add_f32_e32 v12, 1.0, v12
	v_rcp_f32_e32 v12, v12
	s_nop 0
	v_mul_f32_e32 v12, v13, v12
	v_mul_f32_e32 v9, v12, v9
	v_mul_f32_e32 v12, 0xbfb8aa3b, v14
	v_exp_f32_e32 v12, v12
	s_nop 0
	v_add_f32_e32 v12, 1.0, v12
	v_rcp_f32_e32 v12, v12
	s_nop 0
	v_mul_f32_e32 v12, v14, v12
	v_mul_f32_e32 v10, v12, v10
	v_mul_f32_e32 v12, 0xbfb8aa3b, v15
	v_exp_f32_e32 v12, v12
	s_nop 0
	v_add_f32_e32 v12, 1.0, v12
	v_rcp_f32_e32 v12, v12
	s_nop 0
	v_mul_f32_e32 v12, v15, v12
	v_mul_f32_e32 v11, v12, v11
	v_mul_f32_e32 v12, 0xbfb8aa3b, v4
	v_exp_f32_e32 v12, v12
	s_nop 0
	v_add_f32_e32 v12, 1.0, v12
	v_rcp_f32_e32 v12, v12
	s_nop 0
	v_mul_f32_e32 v4, v4, v12
	v_mul_f32_e32 v4, v4, v0
	v_mul_f32_e32 v0, 0xbfb8aa3b, v5
	v_exp_f32_e32 v0, v0
	s_nop 0
	v_add_f32_e32 v0, 1.0, v0
	v_rcp_f32_e32 v0, v0
	s_nop 0
	v_mul_f32_e32 v0, v5, v0
	v_mul_f32_e32 v5, v0, v1
	v_mul_f32_e32 v0, 0xbfb8aa3b, v6
	v_exp_f32_e32 v0, v0
	s_nop 0
	v_add_f32_e32 v0, 1.0, v0
	v_rcp_f32_e32 v0, v0
	s_nop 0
	v_mul_f32_e32 v0, v6, v0
	v_mul_f32_e32 v6, v0, v2
	v_mul_f32_e32 v0, 0xbfb8aa3b, v7
	v_exp_f32_e32 v0, v0
	s_nop 0
	v_add_f32_e32 v0, 1.0, v0
	v_rcp_f32_e32 v0, v0
	s_nop 0
	v_mul_f32_e32 v0, v7, v0
	v_mul_f32_e32 v3, v0, v3
	v_cvt_pk_bf16_f32 v0, v8, v9
	v_cvt_pk_bf16_f32 v1, v10, v11
	v_cvt_pk_bf16_f32 v2, v4, v5
	v_add_u32_e32 v4, 0xb0, v144
	v_mad_i64_i32 v[4:5], s[28:29], v4, s76, v[114:115]
	v_lshl_add_u64 v[4:5], v[4:5], 0, v[116:117]
	s_mov_b64 s[28:29], -1
	v_cvt_pk_bf16_f32 v3, v6, v3
	global_store_dwordx4 v[4:5], v[0:3], off nt
	s_cbranch_vccnz .LBB0_916
	s_andn2_b64 vcc, exec, s[14:15]
	s_cbranch_vccnz .LBB0_915
	s_barrier
	s_branch .LBB0_915

.LBB0_997:
	v_lshl_add_u32 v148, s84, 8, v202
	v_ashrrev_i32_e32 v149, 31, v148
	v_lshl_or_b32 v146, s85, 8, v204
	v_lshlrev_b64 v[148:149], 12, v[148:149]
	v_ashrrev_i32_e32 v147, 31, v146
	v_lshl_add_u64 v[148:149], s[4:5], 0, v[148:149]
	v_lshl_add_u64 v[206:207], v[146:147], 1, v[148:149]
	v_add_co_u32_e32 v216, vcc, s67, v206
	s_lshl_b64 s[26:27], s[26:27], 2
	s_nop 0
	v_addc_co_u32_e32 v217, vcc, 0, v207, vcc
	v_add_co_u32_e32 v252, vcc, s17, v206
	s_add_u32 s26, s51, s26
	s_nop 0
	v_addc_co_u32_e32 v253, vcc, 0, v207, vcc
	v_add_co_u32_e32 v200, vcc, s74, v206
	s_addc_u32 s27, s52, s27
	s_nop 0
	v_addc_co_u32_e32 v201, vcc, 0, v207, vcc
	v_add_co_u32_e32 v198, vcc, s64, v206
	v_lshl_add_u64 v[134:135], v[146:147], 2, s[26:27]
	s_nop 0
	v_addc_co_u32_e32 v199, vcc, 0, v207, vcc
	v_add_co_u32_e32 v196, vcc, s31, v206
	s_mov_b32 s26, 0xb0000
	s_nop 0
	v_addc_co_u32_e32 v197, vcc, 0, v207, vcc
	v_add_co_u32_e32 v194, vcc, s65, v206
	global_load_dwordx4 v[138:141], v[134:135], off offset:16
	global_load_dwordx4 v[142:145], v[134:135], off
	global_load_dwordx4 v[130:133], v[134:135], off offset:528
	s_nop 0
	global_load_dwordx4 v[134:137], v[134:135], off offset:512
	v_addc_co_u32_e32 v195, vcc, 0, v207, vcc
	v_add_co_u32_e32 v192, vcc, s26, v206
	global_load_dwordx4 v[224:227], v[206:207], off
	global_load_dwordx4 v[228:231], v[206:207], off offset:256
	v_addc_co_u32_e32 v193, vcc, 0, v207, vcc
	global_load_dwordx4 v[232:235], v[216:217], off
	global_load_dwordx4 v[236:239], v[216:217], off offset:256
	global_load_dwordx4 v[240:243], v[252:253], off
	global_load_dwordx4 v[244:247], v[252:253], off offset:256
	global_load_dwordx4 v[248:251], v[200:201], off
	global_load_dwordx4 v[178:181], v[200:201], off offset:256
	global_load_dwordx4 v[174:177], v[198:199], off
	global_load_dwordx4 v[170:173], v[198:199], off offset:256
	global_load_dwordx4 v[166:169], v[196:197], off
	global_load_dwordx4 v[162:165], v[196:197], off offset:256
	global_load_dwordx4 v[158:161], v[194:195], off
	global_load_dwordx4 v[154:157], v[194:195], off offset:256
	global_load_dwordx4 v[150:153], v[192:193], off
	global_load_dwordx4 v[146:149], v[192:193], off offset:256
	s_waitcnt vmcnt(0)
	v_lshlrev_b32_e32 v223, 16, v224
	v_fmac_f32_e32 v223, v126, v142
	v_and_b32_e32 v126, 0xffff0000, v224
	v_fmac_f32_e32 v126, v127, v143
	v_lshlrev_b32_e32 v127, 16, v225
	v_fmac_f32_e32 v127, v128, v144
	v_and_b32_e32 v128, 0xffff0000, v225
	v_fmac_f32_e32 v128, v129, v145
	v_cvt_pk_bf16_f32 v126, v223, v126
	v_cvt_pk_bf16_f32 v127, v127, v128
	v_lshlrev_b32_e32 v128, 16, v226
	v_fmac_f32_e32 v128, v122, v138
	v_and_b32_e32 v122, 0xffff0000, v226
	v_fmac_f32_e32 v122, v123, v139
	v_cvt_pk_bf16_f32 v128, v128, v122
	v_lshlrev_b32_e32 v122, 16, v227
	v_fmac_f32_e32 v122, v124, v140
	v_and_b32_e32 v123, 0xffff0000, v227
	v_fmac_f32_e32 v123, v125, v141
	v_cvt_pk_bf16_f32 v129, v122, v123
	v_lshlrev_b32_e32 v122, 16, v228
	v_fmac_f32_e32 v122, v118, v134
	v_and_b32_e32 v118, 0xffff0000, v228
	v_fmac_f32_e32 v118, v119, v135
	v_lshlrev_b32_e32 v119, 16, v229
	v_fmac_f32_e32 v119, v120, v136
	v_and_b32_e32 v120, 0xffff0000, v229
	v_fmac_f32_e32 v120, v121, v137
	global_store_dwordx4 v[206:207], v[126:129], off nt
	v_cvt_pk_bf16_f32 v118, v122, v118
	v_cvt_pk_bf16_f32 v119, v119, v120
	v_lshlrev_b32_e32 v120, 16, v230
	v_fmac_f32_e32 v120, v110, v130
	v_and_b32_e32 v110, 0xffff0000, v230
	v_fmac_f32_e32 v110, v111, v131
	v_cvt_pk_bf16_f32 v120, v120, v110
	v_lshlrev_b32_e32 v110, 16, v231
	v_and_b32_e32 v111, 0xffff0000, v231
	v_fmac_f32_e32 v110, v112, v132
	v_fmac_f32_e32 v111, v113, v133
	v_cvt_pk_bf16_f32 v121, v110, v111
	v_lshlrev_b32_e32 v110, 16, v232
	v_and_b32_e32 v111, 0xffff0000, v232
	v_fmac_f32_e32 v110, v114, v142
	v_fmac_f32_e32 v111, v115, v143
	global_store_dwordx4 v[206:207], v[118:121], off offset:256 nt
	v_cvt_pk_bf16_f32 v110, v110, v111
	v_lshlrev_b32_e32 v111, 16, v233
	v_and_b32_e32 v112, 0xffff0000, v233
	v_fmac_f32_e32 v111, v116, v144
	v_fmac_f32_e32 v112, v117, v145
	v_cvt_pk_bf16_f32 v111, v111, v112
	v_lshlrev_b32_e32 v112, 16, v234
	v_fmac_f32_e32 v112, v106, v138
	v_and_b32_e32 v106, 0xffff0000, v234
	v_fmac_f32_e32 v106, v107, v139
	v_cvt_pk_bf16_f32 v112, v112, v106
	v_lshlrev_b32_e32 v106, 16, v235
	v_fmac_f32_e32 v106, v108, v140
	v_and_b32_e32 v107, 0xffff0000, v235
	v_fmac_f32_e32 v107, v109, v141
	v_cvt_pk_bf16_f32 v113, v106, v107
	v_lshlrev_b32_e32 v106, 16, v236
	v_fmac_f32_e32 v106, v102, v134
	v_and_b32_e32 v102, 0xffff0000, v236
	v_fmac_f32_e32 v102, v103, v135
	v_lshlrev_b32_e32 v103, 16, v237
	v_fmac_f32_e32 v103, v104, v136
	v_and_b32_e32 v104, 0xffff0000, v237
	v_fmac_f32_e32 v104, v105, v137
	global_store_dwordx4 v[216:217], v[110:113], off nt
	v_cvt_pk_bf16_f32 v102, v106, v102
	v_cvt_pk_bf16_f32 v103, v103, v104
	v_lshlrev_b32_e32 v104, 16, v238
	v_fmac_f32_e32 v104, v94, v130
	v_and_b32_e32 v94, 0xffff0000, v238
	v_fmac_f32_e32 v94, v95, v131
	v_cvt_pk_bf16_f32 v104, v104, v94
	v_lshlrev_b32_e32 v94, 16, v239
	v_and_b32_e32 v95, 0xffff0000, v239
	v_fmac_f32_e32 v94, v96, v132
	v_fmac_f32_e32 v95, v97, v133
	v_cvt_pk_bf16_f32 v105, v94, v95
	v_lshlrev_b32_e32 v94, 16, v240
	v_and_b32_e32 v95, 0xffff0000, v240
	v_fmac_f32_e32 v94, v98, v142
	v_fmac_f32_e32 v95, v99, v143
	global_store_dwordx4 v[216:217], v[102:105], off offset:256 nt
	v_cvt_pk_bf16_f32 v94, v94, v95
	v_lshlrev_b32_e32 v95, 16, v241
	v_and_b32_e32 v96, 0xffff0000, v241
	v_fmac_f32_e32 v95, v100, v144
	v_fmac_f32_e32 v96, v101, v145
	v_cvt_pk_bf16_f32 v95, v95, v96
	v_lshlrev_b32_e32 v96, 16, v242
	v_fmac_f32_e32 v96, v90, v138
	v_and_b32_e32 v90, 0xffff0000, v242
	v_fmac_f32_e32 v90, v91, v139
	v_cvt_pk_bf16_f32 v96, v96, v90
	v_lshlrev_b32_e32 v90, 16, v243
	v_fmac_f32_e32 v90, v92, v140
	v_and_b32_e32 v91, 0xffff0000, v243
	v_fmac_f32_e32 v91, v93, v141
	v_cvt_pk_bf16_f32 v97, v90, v91
	v_lshlrev_b32_e32 v90, 16, v244
	v_fmac_f32_e32 v90, v86, v134
	v_and_b32_e32 v86, 0xffff0000, v244
	v_fmac_f32_e32 v86, v87, v135
	v_lshlrev_b32_e32 v87, 16, v245
	v_fmac_f32_e32 v87, v88, v136
	v_and_b32_e32 v88, 0xffff0000, v245
	v_fmac_f32_e32 v88, v89, v137
	global_store_dwordx4 v[252:253], v[94:97], off nt
	v_cvt_pk_bf16_f32 v86, v90, v86
	v_cvt_pk_bf16_f32 v87, v87, v88
	v_lshlrev_b32_e32 v88, 16, v246
	v_fmac_f32_e32 v88, v78, v130
	v_and_b32_e32 v78, 0xffff0000, v246
	v_fmac_f32_e32 v78, v79, v131
	v_cvt_pk_bf16_f32 v88, v88, v78
	v_lshlrev_b32_e32 v78, 16, v247
	v_and_b32_e32 v79, 0xffff0000, v247
	v_fmac_f32_e32 v78, v80, v132
	v_fmac_f32_e32 v79, v81, v133
	v_cvt_pk_bf16_f32 v89, v78, v79
	v_lshlrev_b32_e32 v78, 16, v248
	v_and_b32_e32 v79, 0xffff0000, v248
	v_fmac_f32_e32 v78, v82, v142
	v_fmac_f32_e32 v79, v83, v143
	global_store_dwordx4 v[252:253], v[86:89], off offset:256 nt
	v_cvt_pk_bf16_f32 v78, v78, v79
	v_lshlrev_b32_e32 v79, 16, v249
	v_and_b32_e32 v80, 0xffff0000, v249
	v_fmac_f32_e32 v79, v84, v144
	v_fmac_f32_e32 v80, v85, v145
	v_cvt_pk_bf16_f32 v79, v79, v80
	v_lshlrev_b32_e32 v80, 16, v250
	v_fmac_f32_e32 v80, v74, v138
	v_and_b32_e32 v74, 0xffff0000, v250
	v_fmac_f32_e32 v74, v75, v139
	v_cvt_pk_bf16_f32 v80, v80, v74
	v_lshlrev_b32_e32 v74, 16, v251
	v_fmac_f32_e32 v74, v76, v140
	v_and_b32_e32 v75, 0xffff0000, v251
	v_fmac_f32_e32 v75, v77, v141
	v_cvt_pk_bf16_f32 v81, v74, v75
	v_lshlrev_b32_e32 v74, 16, v178
	v_fmac_f32_e32 v74, v70, v134
	v_and_b32_e32 v70, 0xffff0000, v178
	v_fmac_f32_e32 v70, v71, v135
	v_lshlrev_b32_e32 v71, 16, v179
	v_fmac_f32_e32 v71, v72, v136
	v_and_b32_e32 v72, 0xffff0000, v179
	v_fmac_f32_e32 v72, v73, v137
	global_store_dwordx4 v[200:201], v[78:81], off nt
	v_cvt_pk_bf16_f32 v70, v74, v70
	v_cvt_pk_bf16_f32 v71, v71, v72
	v_lshlrev_b32_e32 v72, 16, v180
	v_fmac_f32_e32 v72, v66, v130
	v_and_b32_e32 v66, 0xffff0000, v180
	v_fmac_f32_e32 v66, v67, v131
	v_cvt_pk_bf16_f32 v72, v72, v66
	v_lshlrev_b32_e32 v66, 16, v181
	v_fmac_f32_e32 v66, v68, v132
	v_and_b32_e32 v67, 0xffff0000, v181
	v_fmac_f32_e32 v67, v69, v133
	v_cvt_pk_bf16_f32 v73, v66, v67
	v_lshlrev_b32_e32 v66, 16, v174
	v_fmac_f32_e32 v66, v62, v142
	v_and_b32_e32 v62, 0xffff0000, v174
	v_fmac_f32_e32 v62, v63, v143
	v_lshlrev_b32_e32 v63, 16, v175
	v_fmac_f32_e32 v63, v64, v144
	v_and_b32_e32 v64, 0xffff0000, v175
	v_fmac_f32_e32 v64, v65, v145
	global_store_dwordx4 v[200:201], v[70:73], off offset:256 nt
	v_cvt_pk_bf16_f32 v62, v66, v62
	v_cvt_pk_bf16_f32 v63, v63, v64
	v_lshlrev_b32_e32 v64, 16, v176
	v_fmac_f32_e32 v64, v58, v138
	v_and_b32_e32 v58, 0xffff0000, v176
	v_fmac_f32_e32 v58, v59, v139
	v_cvt_pk_bf16_f32 v64, v64, v58
	v_lshlrev_b32_e32 v58, 16, v177
	v_fmac_f32_e32 v58, v60, v140
	v_and_b32_e32 v59, 0xffff0000, v177
	v_fmac_f32_e32 v59, v61, v141
	v_cvt_pk_bf16_f32 v65, v58, v59
	v_lshlrev_b32_e32 v58, 16, v170
	v_fmac_f32_e32 v58, v54, v134
	v_and_b32_e32 v54, 0xffff0000, v170
	v_fmac_f32_e32 v54, v55, v135
	v_lshlrev_b32_e32 v55, 16, v171
	v_fmac_f32_e32 v55, v56, v136
	v_and_b32_e32 v56, 0xffff0000, v171
	v_fmac_f32_e32 v56, v57, v137
	global_store_dwordx4 v[198:199], v[62:65], off nt
	v_cvt_pk_bf16_f32 v54, v58, v54
	v_cvt_pk_bf16_f32 v55, v55, v56
	v_lshlrev_b32_e32 v56, 16, v172
	v_fmac_f32_e32 v56, v46, v130
	v_and_b32_e32 v46, 0xffff0000, v172
	v_fmac_f32_e32 v46, v47, v131
	v_cvt_pk_bf16_f32 v56, v56, v46
	v_lshlrev_b32_e32 v46, 16, v173
	v_and_b32_e32 v47, 0xffff0000, v173
	v_fmac_f32_e32 v46, v48, v132
	v_fmac_f32_e32 v47, v49, v133
	v_cvt_pk_bf16_f32 v57, v46, v47
	v_lshlrev_b32_e32 v46, 16, v166
	v_and_b32_e32 v47, 0xffff0000, v166
	v_fmac_f32_e32 v46, v50, v142
	v_fmac_f32_e32 v47, v51, v143
	global_store_dwordx4 v[198:199], v[54:57], off offset:256 nt
	v_cvt_pk_bf16_f32 v46, v46, v47
	v_lshlrev_b32_e32 v47, 16, v167
	v_and_b32_e32 v48, 0xffff0000, v167
	v_fmac_f32_e32 v47, v52, v144
	v_fmac_f32_e32 v48, v53, v145
	v_cvt_pk_bf16_f32 v47, v47, v48
	v_lshlrev_b32_e32 v48, 16, v168
	v_fmac_f32_e32 v48, v42, v138
	v_and_b32_e32 v42, 0xffff0000, v168
	v_fmac_f32_e32 v42, v43, v139
	v_cvt_pk_bf16_f32 v48, v48, v42
	v_lshlrev_b32_e32 v42, 16, v169
	v_fmac_f32_e32 v42, v44, v140
	v_and_b32_e32 v43, 0xffff0000, v169
	v_fmac_f32_e32 v43, v45, v141
	v_cvt_pk_bf16_f32 v49, v42, v43
	v_lshlrev_b32_e32 v42, 16, v162
	v_fmac_f32_e32 v42, v38, v134
	v_and_b32_e32 v38, 0xffff0000, v162
	v_fmac_f32_e32 v38, v39, v135
	v_lshlrev_b32_e32 v39, 16, v163
	v_fmac_f32_e32 v39, v40, v136
	v_and_b32_e32 v40, 0xffff0000, v163
	v_fmac_f32_e32 v40, v41, v137
	global_store_dwordx4 v[196:197], v[46:49], off nt
	v_cvt_pk_bf16_f32 v38, v42, v38
	v_cvt_pk_bf16_f32 v39, v39, v40
	v_lshlrev_b32_e32 v40, 16, v164
	v_fmac_f32_e32 v40, v30, v130
	v_and_b32_e32 v30, 0xffff0000, v164
	v_fmac_f32_e32 v30, v31, v131
	v_cvt_pk_bf16_f32 v40, v40, v30
	v_lshlrev_b32_e32 v30, 16, v165
	v_and_b32_e32 v31, 0xffff0000, v165
	v_fmac_f32_e32 v30, v32, v132
	v_fmac_f32_e32 v31, v33, v133
	v_cvt_pk_bf16_f32 v41, v30, v31
	v_lshlrev_b32_e32 v30, 16, v158
	v_and_b32_e32 v31, 0xffff0000, v158
	v_fmac_f32_e32 v30, v34, v142
	v_fmac_f32_e32 v31, v35, v143
	global_store_dwordx4 v[196:197], v[38:41], off offset:256 nt
	v_cvt_pk_bf16_f32 v30, v30, v31
	v_lshlrev_b32_e32 v31, 16, v159
	v_and_b32_e32 v32, 0xffff0000, v159
	v_fmac_f32_e32 v31, v36, v144
	v_fmac_f32_e32 v32, v37, v145
	v_cvt_pk_bf16_f32 v31, v31, v32
	v_lshlrev_b32_e32 v32, 16, v160
	v_fmac_f32_e32 v32, v26, v138
	v_and_b32_e32 v26, 0xffff0000, v160
	v_fmac_f32_e32 v26, v27, v139
	v_cvt_pk_bf16_f32 v32, v32, v26
	v_lshlrev_b32_e32 v26, 16, v161
	v_fmac_f32_e32 v26, v28, v140
	v_and_b32_e32 v27, 0xffff0000, v161
	v_fmac_f32_e32 v27, v29, v141
	v_cvt_pk_bf16_f32 v33, v26, v27
	v_lshlrev_b32_e32 v26, 16, v154
	v_fmac_f32_e32 v26, v22, v134
	v_and_b32_e32 v22, 0xffff0000, v154
	v_fmac_f32_e32 v22, v23, v135
	v_lshlrev_b32_e32 v23, 16, v155
	v_fmac_f32_e32 v23, v24, v136
	v_and_b32_e32 v24, 0xffff0000, v155
	v_fmac_f32_e32 v24, v25, v137
	global_store_dwordx4 v[194:195], v[30:33], off nt
	v_cvt_pk_bf16_f32 v22, v26, v22
	v_cvt_pk_bf16_f32 v23, v23, v24
	v_lshlrev_b32_e32 v24, 16, v156
	v_fmac_f32_e32 v24, v12, v130
	v_and_b32_e32 v12, 0xffff0000, v156
	v_fmac_f32_e32 v12, v13, v131
	v_cvt_pk_bf16_f32 v24, v24, v12
	v_lshlrev_b32_e32 v12, 16, v157
	v_and_b32_e32 v13, 0xffff0000, v157
	v_fmac_f32_e32 v12, v14, v132
	v_fmac_f32_e32 v13, v15, v133
	v_cvt_pk_bf16_f32 v25, v12, v13
	v_lshlrev_b32_e32 v12, 16, v150
	v_and_b32_e32 v13, 0xffff0000, v150
	v_fmac_f32_e32 v12, v18, v142
	v_fmac_f32_e32 v13, v19, v143
	global_store_dwordx4 v[194:195], v[22:25], off offset:256 nt
	v_cvt_pk_bf16_f32 v12, v12, v13
	v_lshlrev_b32_e32 v13, 16, v151
	v_and_b32_e32 v14, 0xffff0000, v151
	v_fmac_f32_e32 v13, v20, v144
	v_fmac_f32_e32 v14, v21, v145
	v_cvt_pk_bf16_f32 v13, v13, v14
	v_lshlrev_b32_e32 v14, 16, v152
	v_fmac_f32_e32 v14, v8, v138
	v_and_b32_e32 v8, 0xffff0000, v152
	v_fmac_f32_e32 v8, v9, v139
	v_cvt_pk_bf16_f32 v14, v14, v8
	v_lshlrev_b32_e32 v8, 16, v153
	v_fmac_f32_e32 v8, v10, v140
	v_and_b32_e32 v9, 0xffff0000, v153
	v_fmac_f32_e32 v9, v11, v141
	v_cvt_pk_bf16_f32 v15, v8, v9
	v_lshlrev_b32_e32 v8, 16, v146
	v_fmac_f32_e32 v8, v4, v134
	v_and_b32_e32 v4, 0xffff0000, v146
	v_fmac_f32_e32 v4, v5, v135
	v_lshlrev_b32_e32 v5, 16, v147
	v_fmac_f32_e32 v5, v6, v136
	v_and_b32_e32 v6, 0xffff0000, v147
	v_fmac_f32_e32 v6, v7, v137
	global_store_dwordx4 v[192:193], v[12:15], off nt
	v_cvt_pk_bf16_f32 v4, v8, v4
	v_cvt_pk_bf16_f32 v5, v5, v6
	v_lshlrev_b32_e32 v6, 16, v148
	v_fmac_f32_e32 v6, v0, v130
	v_and_b32_e32 v0, 0xffff0000, v148
	v_fmac_f32_e32 v0, v1, v131
	v_cvt_pk_bf16_f32 v6, v6, v0
	v_lshlrev_b32_e32 v0, 16, v149
	v_and_b32_e32 v1, 0xffff0000, v149
	s_and_b64 vcc, exec, s[38:39]
	s_mov_b64 s[26:27], -1
	v_fmac_f32_e32 v0, v2, v132
	v_fmac_f32_e32 v1, v3, v133
	v_cvt_pk_bf16_f32 v7, v0, v1
	global_store_dwordx4 v[192:193], v[4:7], off offset:256 nt
	s_cbranch_vccnz .LBB0_984
	s_andn2_b64 vcc, exec, s[0:1]
	s_cbranch_vccnz .LBB0_983
	s_barrier
	s_branch .LBB0_983
